# attention epilogues: pair bf16 short stores into dword stores via DPP quad_perm + v_perm (64 -> 32 stores per lane per item), counted vmcnt re-derived
# baseline (speedup 1.0000x reference)
; DI unsigned f2bf(float f) { unsigned u = __builtin_bit_cast(unsigned, f); return (u + 0x7fffu + ((u >> 16) & 1u)) >> 16; }
; DI float shx(float v, int o, int lane) { return __int_as_float(__builtin_amdgcn_ds_bpermute((lane ^ o) << 2, __float_as_int(v))); }
; DI int crow(int i, int hh) { return (i & 3) + 8 * (i >> 2) + 4 * hh; }
; DI void attn_item(CArgs& a, LAS unsigned char* lds, int l, int b, int h, int qb, int tid_, int wave, int lane_) {
;     ...
;     const float ltot = l_run + shx(l_run, 32, lane);
;     if (hh == 0) scr[r] = 1.f / ltot;
;     asm volatile("s_waitcnt lgkmcnt(0)" ::: "memory");
;     bf16_t* mix = (bf16_t*)(a.ws + WS_BUFA);
;     const size_t trow0 = (size_t)b * S_ + qb * 256 + wave * 32;
; #pragma unroll
;     for (int i = 0; i < 16; ++i) { const float inv = scr[crow(i, hh)]; float s = 0.f;
; #pragma unroll
;         for (int vt = 0; vt < 4; ++vt) { o[vt][i] *= inv; s += o[vt][i] * o[vt][i]; }
;         s += shx(s, 1, lane); s += shx(s, 2, lane); s += shx(s, 4, lane); s += shx(s, 8, lane); s += shx(s, 16, lane);
;         const float rs = rsqrtf(s * (1.f / 128.f) + EPS);
; #pragma unroll
;         for (int vt = 0; vt < 4; ++vt) { const int col = h * 128 + 32 * vt + r; mix[(trow0 + crow(i, hh)) * DM + 1024 + col] = (bf16_t)f2bf(o[vt][i] * rs * a.in[I_MIXG][l * DM + 1024 + col]); } }
.LBB0_294:
	s_or_b64 exec, exec, s[0:1]
	s_mov_b32 s98, 0x7060302
	s_mov_b32 s100, 0xaaaaaaaa
	s_mov_b32 s101, 0xaaaaaaaa
	v_mbcnt_lo_u32_b32 v90, -1, 0
	v_mbcnt_hi_u32_b32 v90, -1, v90
	v_and_b32_e32 v90, 1, v90
	v_mul_u32_u24_e32 v90, 62, v90
	v_mov_b32_e32 v91, 0
	s_waitcnt lgkmcnt(0)
	v_lshl_add_u32 v74, v195, 2, s27
	ds_read_b128 v[76:79], v74
	v_or_b32_e32 v70, s43, v169
	s_or_b32 s0, s14, s5
	v_or_b32_e32 v80, s92, v70
	s_add_u32 s0, s0, s26
	s_waitcnt lgkmcnt(1)
	v_mov_b32_e32 v64, v0
	v_mov_b32_e32 v65, v16
	v_lshl_add_u64 v[106:107], v[80:81], 2, s[8:9]
	s_addc_u32 s1, s15, s40
	s_waitcnt lgkmcnt(0)
	v_pk_mul_f32 v[98:99], v[64:65], v[76:77] op_sel_hi:[1,0]
	v_mov_b32_e32 v64, v48
	v_mov_b32_e32 v65, v32
	v_add_co_u32_e32 v106, vcc, s49, v106
	v_pk_mul_f32 v[102:103], v[64:65], v[76:77] op_sel_hi:[1,0]
	v_or_b32_e32 v64, s0, v195
	v_mov_b32_e32 v65, s1
	v_addc_co_u32_e32 v107, vcc, 0, v107, vcc
	v_lshlrev_b64 v[68:69], 12, v[64:65]
	global_load_dword v48, v[106:107], off
	v_lshl_add_u64 v[68:69], s[12:13], 0, v[68:69]
	v_lshlrev_b32_e32 v80, 1, v70
	v_lshl_add_u64 v[106:107], v[68:69], 0, v[80:81]
	v_add_u32_e32 v68, s92, v70
	v_mov_b32_e32 v69, v81
	v_lshl_add_u64 v[68:69], v[68:69], 2, s[8:9]
	v_add_co_u32_e32 v108, vcc, s49, v68
	v_mov_b32_e32 v16, v1
	s_nop 0
	v_addc_co_u32_e32 v109, vcc, 0, v69, vcc
	global_load_dword v68, v[108:109], off offset:128
	global_load_dword v70, v[108:109], off offset:256
	global_load_dword v69, v[108:109], off offset:384
	v_pk_mul_f32 v[0:1], v[16:17], v[76:77] op_sel:[0,1]
	v_mov_b32_e32 v32, v49
	v_pk_mul_f32 v[100:101], v[98:99], v[98:99]
	v_pk_mul_f32 v[16:17], v[0:1], v[0:1]
	v_pk_mul_f32 v[32:33], v[32:33], v[76:77] op_sel:[0,1]
	v_pk_mul_f32 v[104:105], v[102:103], v[102:103]
	v_pk_mul_f32 v[76:77], v[32:33], v[32:33]
	v_mov_b32_e32 v108, v16
	v_mov_b32_e32 v109, v100
	v_mov_b32_e32 v100, v17
	v_pk_add_f32 v[16:17], v[108:109], v[100:101]
	v_mov_b32_e32 v100, v77
	v_mov_b32_e32 v101, v105
	v_pk_add_f32 v[16:17], v[100:101], v[16:17]
	v_mov_b32_e32 v77, v104
	v_xor_b32_e32 v73, 4, v196
	v_pk_add_f32 v[16:17], v[76:77], v[16:17]
	ds_bpermute_b32 v77, v73, v17
	ds_bpermute_b32 v76, v73, v16
	v_xor_b32_e32 v72, 8, v196
	v_xor_b32_e32 v71, 16, v196
	v_xor_b32_e32 v67, 32, v196
	v_xor_b32_e32 v66, 64, v196
	s_waitcnt lgkmcnt(0)
	v_pk_add_f32 v[16:17], v[16:17], v[76:77]
	ds_bpermute_b32 v77, v72, v17
	ds_bpermute_b32 v76, v72, v16
	v_or_b32_e32 v100, 2, v64
	v_mov_b32_e32 v101, s1
	v_lshlrev_b64 v[100:101], 12, v[100:101]
	v_lshl_add_u64 v[100:101], s[12:13], 0, v[100:101]
	s_waitcnt lgkmcnt(0)
	v_pk_add_f32 v[16:17], v[16:17], v[76:77]
	ds_bpermute_b32 v77, v71, v17
	ds_bpermute_b32 v76, v71, v16
	v_lshl_add_u64 v[100:101], v[100:101], 0, v[80:81]
	s_add_i32 s42, s42, s72
	s_add_i32 s41, s41, s72
	s_cmpk_gt_i32 s42, 0xff
	s_waitcnt lgkmcnt(0)
	v_pk_add_f32 v[16:17], v[16:17], v[76:77]
	ds_bpermute_b32 v77, v67, v17
	ds_bpermute_b32 v76, v67, v16
	s_waitcnt lgkmcnt(0)
	v_pk_add_f32 v[16:17], v[16:17], v[76:77]
	ds_bpermute_b32 v77, v66, v17
	ds_bpermute_b32 v76, v66, v16
	s_waitcnt lgkmcnt(0)
	v_pk_add_f32 v[76:77], v[16:17], v[76:77]
	v_mov_b64_e32 v[16:17], s[76:77]
	v_pk_fma_f32 v[76:77], v[76:77], s[78:79], v[16:17] op_sel_hi:[1,0,0]
	s_nop 0
	v_mul_f32_e32 v49, 0x4b800000, v77
	v_cmp_gt_f32_e64 s[6:7], s64, v77
	v_cmp_gt_f32_e32 vcc, s64, v76
	s_nop 0
	v_cndmask_b32_e64 v49, v77, v49, s[6:7]
	v_rsq_f32_e32 v49, v49
	s_nop 0
	v_mul_f32_e32 v75, 0x45800000, v49
	v_cndmask_b32_e64 v49, v49, v75, s[6:7]
	v_mul_f32_e32 v75, v98, v49
	s_waitcnt vmcnt(3)
	v_mul_f32_e32 v75, v48, v75
	v_bfe_u32 v77, v75, 16, 1
	v_add3_u32 v75, v75, v77, s33
	v_mov_b32_e32 v82, v75
	v_mul_f32_e32 v75, v99, v49
	s_waitcnt vmcnt(2)
	v_mul_f32_e32 v75, v68, v75
	v_bfe_u32 v77, v75, 16, 1
	v_add3_u32 v75, v75, v77, s33
	s_nop 1
	v_mov_b32_dpp v83, v82 quad_perm:[1,0,3,2] row_mask:0xf bank_mask:0xf
	v_mov_b32_dpp v84, v75 quad_perm:[1,0,3,2] row_mask:0xf bank_mask:0xf
	v_perm_b32 v85, v83, v82, s98
	v_perm_b32 v86, v75, v84, s98
	v_cndmask_b32_e64 v85, v85, v86, s[100:101]
	v_lshl_add_u64 v[88:89], v[106:107], 0, v[90:91]
	global_store_dword v[88:89], v85, off
	v_mul_f32_e32 v75, v103, v49
	s_waitcnt vmcnt(2)
	v_mul_f32_e32 v75, v70, v75
	v_bfe_u32 v77, v75, 16, 1
	v_mul_f32_e32 v49, v102, v49
	v_add3_u32 v75, v75, v77, s33
	s_waitcnt vmcnt(1)
; DI unsigned f2bf(float f) { unsigned u = __builtin_bit_cast(unsigned, f); return (u + 0x7fffu + ((u >> 16) & 1u)) >> 16; }
; DI float shx(float v, int o, int lane) { return __int_as_float(__builtin_amdgcn_ds_bpermute((lane ^ o) << 2, __float_as_int(v))); }
; DI int crow(int i, int hh) { return (i & 3) + 8 * (i >> 2) + 4 * hh; }
; DI void attn_item(CArgs& a, LAS unsigned char* lds, int l, int b, int h, int qb, int tid_, int wave, int lane_) {
;     ...
;     for (int i = 0; i < 16; ++i) { const float inv = scr[crow(i, hh)]; float s = 0.f;
; #pragma unroll
;         for (int vt = 0; vt < 4; ++vt) { o[vt][i] *= inv; s += o[vt][i] * o[vt][i]; }
;         s += shx(s, 1, lane); s += shx(s, 2, lane); s += shx(s, 4, lane); s += shx(s, 8, lane); s += shx(s, 16, lane);
;         const float rs = rsqrtf(s * (1.f / 128.f) + EPS);
; #pragma unroll
;         for (int vt = 0; vt < 4; ++vt) { const int col = h * 128 + 32 * vt + r; mix[(trow0 + crow(i, hh)) * DM + 1024 + col] = (bf16_t)f2bf(o[vt][i] * rs * a.in[I_MIXG][l * DM + 1024 + col]); } }
	v_mul_f32_e32 v49, v69, v49
	v_mov_b32_e32 v82, v75
	v_bfe_u32 v75, v49, 16, 1
	v_add3_u32 v49, v49, v75, s33
	s_nop 1
	v_mov_b32_dpp v83, v82 quad_perm:[1,0,3,2] row_mask:0xf bank_mask:0xf
	v_mov_b32_dpp v84, v49 quad_perm:[1,0,3,2] row_mask:0xf bank_mask:0xf
	v_perm_b32 v85, v83, v82, s98
	v_perm_b32 v86, v49, v84, s98
	v_cndmask_b32_e64 v85, v85, v86, s[100:101]
	v_lshl_add_u64 v[88:89], v[106:107], 0, v[90:91]
	global_store_dword v[88:89], v85, off offset:128
	v_mul_f32_e32 v49, 0x4b800000, v76
	v_cndmask_b32_e32 v49, v76, v49, vcc
	v_rsq_f32_e32 v49, v49
	v_or_b32_e32 v76, 1, v64
	v_mov_b32_e32 v77, s1
	v_lshlrev_b64 v[76:77], 12, v[76:77]
	v_mul_f32_e32 v75, 0x45800000, v49
	v_cndmask_b32_e32 v49, v49, v75, vcc
	v_mul_f32_e32 v0, v0, v49
	v_mul_f32_e32 v0, v48, v0
	v_lshl_add_u64 v[76:77], s[12:13], 0, v[76:77]
	v_bfe_u32 v75, v0, 16, 1
	v_add3_u32 v0, v0, v75, s33
	v_lshl_add_u64 v[76:77], v[76:77], 0, v[80:81]
	v_mov_b32_e32 v82, v0
	v_mul_f32_e32 v0, v1, v49
	v_mul_f32_e32 v0, v68, v0
	v_bfe_u32 v1, v0, 16, 1
	v_add3_u32 v0, v0, v1, s33
	s_nop 1
	v_mov_b32_dpp v83, v82 quad_perm:[1,0,3,2] row_mask:0xf bank_mask:0xf
	v_mov_b32_dpp v84, v0 quad_perm:[1,0,3,2] row_mask:0xf bank_mask:0xf
	v_perm_b32 v85, v83, v82, s98
	v_perm_b32 v86, v0, v84, s98
	v_cndmask_b32_e64 v85, v85, v86, s[100:101]
	v_lshl_add_u64 v[88:89], v[76:77], 0, v[90:91]
	global_store_dword v[88:89], v85, off
	v_mul_f32_e32 v0, v33, v49
	v_mul_f32_e32 v0, v70, v0
	v_bfe_u32 v1, v0, 16, 1
	v_add3_u32 v0, v0, v1, s33
	v_mov_b32_e32 v82, v0
	v_mul_f32_e32 v0, v32, v49
	v_mul_f32_e32 v0, v69, v0
	v_bfe_u32 v1, v0, 16, 1
	v_add3_u32 v0, v0, v1, s33
	s_nop 1
	v_mov_b32_dpp v83, v82 quad_perm:[1,0,3,2] row_mask:0xf bank_mask:0xf
	v_mov_b32_dpp v84, v0 quad_perm:[1,0,3,2] row_mask:0xf bank_mask:0xf
	v_perm_b32 v85, v83, v82, s98
	v_perm_b32 v86, v0, v84, s98
	v_cndmask_b32_e64 v85, v85, v86, s[100:101]
	v_lshl_add_u64 v[88:89], v[76:77], 0, v[90:91]
	global_store_dword v[88:89], v85, off offset:128
	v_mov_b32_e32 v0, v2
	v_mov_b32_e32 v1, v18
	v_mov_b32_e32 v18, v3
	v_mov_b32_e32 v2, v79
	v_pk_mul_f32 v[0:1], v[0:1], v[78:79] op_sel_hi:[1,0]
	v_mov_b32_e32 v76, v50
	v_mov_b32_e32 v77, v34
	v_pk_mul_f32 v[18:19], v[18:19], v[2:3] op_sel_hi:[1,0]
	v_mov_b32_e32 v34, v51
	v_pk_mul_f32 v[32:33], v[0:1], v[0:1]
	v_pk_mul_f32 v[76:77], v[76:77], v[78:79] op_sel_hi:[1,0]
	v_pk_mul_f32 v[78:79], v[18:19], v[18:19]
	v_pk_mul_f32 v[2:3], v[34:35], v[2:3] op_sel_hi:[1,0]
	v_pk_mul_f32 v[98:99], v[76:77], v[76:77]
	v_pk_mul_f32 v[34:35], v[2:3], v[2:3]
	v_mov_b32_e32 v50, v78
	v_mov_b32_e32 v51, v32
	v_mov_b32_e32 v32, v79
	v_pk_add_f32 v[32:33], v[50:51], v[32:33]
	v_mov_b32_e32 v50, v35
	v_mov_b32_e32 v51, v99
	v_pk_add_f32 v[32:33], v[50:51], v[32:33]
	v_mov_b32_e32 v35, v98
	v_pk_add_f32 v[32:33], v[34:35], v[32:33]
	ds_bpermute_b32 v35, v73, v33
	ds_bpermute_b32 v34, v73, v32
	s_waitcnt lgkmcnt(0)
	v_pk_add_f32 v[32:33], v[32:33], v[34:35]
	ds_bpermute_b32 v35, v72, v33
	ds_bpermute_b32 v34, v72, v32
	s_waitcnt lgkmcnt(0)
	v_pk_add_f32 v[32:33], v[32:33], v[34:35]
	ds_bpermute_b32 v35, v71, v33
	ds_bpermute_b32 v34, v71, v32
	s_waitcnt lgkmcnt(0)
	v_pk_add_f32 v[32:33], v[32:33], v[34:35]
	ds_bpermute_b32 v35, v67, v33
	ds_bpermute_b32 v34, v67, v32
	s_waitcnt lgkmcnt(0)
	v_pk_add_f32 v[32:33], v[32:33], v[34:35]
	ds_bpermute_b32 v35, v66, v33
	ds_bpermute_b32 v34, v66, v32
	s_waitcnt lgkmcnt(0)
	v_pk_add_f32 v[32:33], v[32:33], v[34:35]
	s_nop 0
	v_pk_fma_f32 v[32:33], v[32:33], s[78:79], v[16:17] op_sel_hi:[1,0,0]
	v_mov_b32_e32 v35, v36
	v_mul_f32_e32 v34, 0x4b800000, v33
	v_cmp_gt_f32_e64 s[6:7], s64, v33
	v_cmp_gt_f32_e32 vcc, s64, v32
	v_mov_b32_e32 v36, v53
	v_cndmask_b32_e64 v33, v33, v34, s[6:7]
	v_rsq_f32_e32 v33, v33
	s_nop 0
	v_mul_f32_e32 v34, 0x45800000, v33
	v_cndmask_b32_e64 v33, v33, v34, s[6:7]
	v_mul_f32_e32 v0, v0, v33
	v_mul_f32_e32 v0, v48, v0
	v_bfe_u32 v34, v0, 16, 1
	v_add3_u32 v0, v0, v34, s33
	v_mov_b32_e32 v82, v0
	v_mul_f32_e32 v0, v1, v33
	v_mul_f32_e32 v0, v68, v0
	v_bfe_u32 v1, v0, 16, 1
	v_add3_u32 v0, v0, v1, s33
	s_nop 1
	v_mov_b32_dpp v83, v82 quad_perm:[1,0,3,2] row_mask:0xf bank_mask:0xf
	v_mov_b32_dpp v84, v0 quad_perm:[1,0,3,2] row_mask:0xf bank_mask:0xf
	v_perm_b32 v85, v83, v82, s98
	v_perm_b32 v86, v0, v84, s98
	v_cndmask_b32_e64 v85, v85, v86, s[100:101]
	v_lshl_add_u64 v[88:89], v[100:101], 0, v[90:91]
	global_store_dword v[88:89], v85, off
	v_mul_f32_e32 v0, v77, v33
	v_mul_f32_e32 v0, v70, v0
	v_bfe_u32 v1, v0, 16, 1
	v_add3_u32 v0, v0, v1, s33
	v_mov_b32_e32 v82, v0
	v_mul_f32_e32 v0, v76, v33
	v_mul_f32_e32 v0, v69, v0
	v_bfe_u32 v1, v0, 16, 1
	v_add3_u32 v0, v0, v1, s33
	s_nop 1
	v_mov_b32_dpp v83, v82 quad_perm:[1,0,3,2] row_mask:0xf bank_mask:0xf
	v_mov_b32_dpp v84, v0 quad_perm:[1,0,3,2] row_mask:0xf bank_mask:0xf
	v_perm_b32 v85, v83, v82, s98
	v_perm_b32 v86, v0, v84, s98
	v_cndmask_b32_e64 v85, v85, v86, s[100:101]
	v_lshl_add_u64 v[88:89], v[100:101], 0, v[90:91]
	global_store_dword v[88:89], v85, off offset:128
	v_mul_f32_e32 v0, 0x4b800000, v32
	v_cndmask_b32_e32 v0, v32, v0, vcc
	v_rsq_f32_e32 v0, v0
	v_mov_b32_e32 v34, v52
	v_or_b32_e32 v76, 8, v64
	v_mov_b32_e32 v77, s1
	v_mul_f32_e32 v1, 0x45800000, v0
	v_cndmask_b32_e32 v32, v0, v1, vcc
	v_or_b32_e32 v0, 3, v64
	v_mov_b32_e32 v1, s1
	v_mul_f32_e32 v18, v18, v32
	v_lshlrev_b64 v[0:1], 12, v[0:1]
	v_mul_f32_e32 v18, v48, v18
	v_lshl_add_u64 v[0:1], s[12:13], 0, v[0:1]
	v_bfe_u32 v33, v18, 16, 1
	v_add3_u32 v18, v18, v33, s33
	v_lshl_add_u64 v[0:1], v[0:1], 0, v[80:81]
	v_mov_b32_e32 v82, v18
	v_mul_f32_e32 v18, v19, v32
	v_mul_f32_e32 v18, v68, v18
	v_bfe_u32 v19, v18, 16, 1
	v_mul_f32_e32 v3, v3, v32
	v_add3_u32 v18, v18, v19, s33
	v_mul_f32_e32 v3, v70, v3
	s_nop 1
	v_mov_b32_dpp v83, v82 quad_perm:[1,0,3,2] row_mask:0xf bank_mask:0xf
	v_mov_b32_dpp v84, v18 quad_perm:[1,0,3,2] row_mask:0xf bank_mask:0xf
	v_perm_b32 v85, v83, v82, s98
	v_perm_b32 v86, v18, v84, s98
	v_cndmask_b32_e64 v85, v85, v86, s[100:101]
	v_lshl_add_u64 v[88:89], v[0:1], 0, v[90:91]
	global_store_dword v[88:89], v85, off
	v_bfe_u32 v18, v3, 16, 1
	v_mul_f32_e32 v2, v2, v32
	v_add3_u32 v3, v3, v18, s33
	v_mul_f32_e32 v2, v69, v2
	v_mov_b32_e32 v82, v3
	v_bfe_u32 v3, v2, 16, 1
	v_add3_u32 v2, v2, v3, s33
	s_nop 1
	v_mov_b32_dpp v83, v82 quad_perm:[1,0,3,2] row_mask:0xf bank_mask:0xf
	v_mov_b32_dpp v84, v2 quad_perm:[1,0,3,2] row_mask:0xf bank_mask:0xf
	v_perm_b32 v85, v83, v82, s98
	v_perm_b32 v86, v2, v84, s98
	v_cndmask_b32_e64 v85, v85, v86, s[100:101]
	v_lshl_add_u64 v[88:89], v[0:1], 0, v[90:91]
	global_store_dword v[88:89], v85, off offset:128
	ds_read_b128 v[0:3], v74 offset:32
	v_mov_b32_e32 v18, v4
	v_mov_b32_e32 v19, v20
	v_mov_b32_e32 v20, v5
	v_lshlrev_b64 v[76:77], 12, v[76:77]
	s_waitcnt lgkmcnt(0)
; DI unsigned f2bf(float f) { unsigned u = __builtin_bit_cast(unsigned, f); return (u + 0x7fffu + ((u >> 16) & 1u)) >> 16; }
; DI float shx(float v, int o, int lane) { return __int_as_float(__builtin_amdgcn_ds_bpermute((lane ^ o) << 2, __float_as_int(v))); }
; DI int crow(int i, int hh) { return (i & 3) + 8 * (i >> 2) + 4 * hh; }
; DI void attn_item(CArgs& a, LAS unsigned char* lds, int l, int b, int h, int qb, int tid_, int wave, int lane_) {
;     ...
;     for (int i = 0; i < 16; ++i) { const float inv = scr[crow(i, hh)]; float s = 0.f;
; #pragma unroll
;         for (int vt = 0; vt < 4; ++vt) { o[vt][i] *= inv; s += o[vt][i] * o[vt][i]; }
;         s += shx(s, 1, lane); s += shx(s, 2, lane); s += shx(s, 4, lane); s += shx(s, 8, lane); s += shx(s, 16, lane);
;         const float rs = rsqrtf(s * (1.f / 128.f) + EPS);
; #pragma unroll
;         for (int vt = 0; vt < 4; ++vt) { const int col = h * 128 + 32 * vt + r; mix[(trow0 + crow(i, hh)) * DM + 1024 + col] = (bf16_t)f2bf(o[vt][i] * rs * a.in[I_MIXG][l * DM + 1024 + col]); } }
	v_pk_mul_f32 v[18:19], v[18:19], v[0:1] op_sel_hi:[1,0]
	v_pk_mul_f32 v[4:5], v[20:21], v[0:1] op_sel:[0,1]
	v_pk_mul_f32 v[32:33], v[18:19], v[18:19]
	v_pk_mul_f32 v[34:35], v[34:35], v[0:1] op_sel_hi:[1,0]
	v_pk_mul_f32 v[20:21], v[4:5], v[4:5]
	v_pk_mul_f32 v[0:1], v[36:37], v[0:1] op_sel:[0,1]
	v_pk_mul_f32 v[50:51], v[34:35], v[34:35]
	v_pk_mul_f32 v[36:37], v[0:1], v[0:1]
	v_mov_b32_e32 v52, v20
	v_mov_b32_e32 v53, v32
	v_mov_b32_e32 v32, v21
	v_pk_add_f32 v[20:21], v[52:53], v[32:33]
	v_mov_b32_e32 v32, v37
	v_mov_b32_e32 v33, v51
	v_pk_add_f32 v[20:21], v[32:33], v[20:21]
	v_mov_b32_e32 v37, v50
	v_pk_add_f32 v[20:21], v[36:37], v[20:21]
	ds_bpermute_b32 v33, v73, v21
	ds_bpermute_b32 v32, v73, v20
	v_lshl_add_u64 v[76:77], s[12:13], 0, v[76:77]
	v_lshl_add_u64 v[76:77], v[76:77], 0, v[80:81]
	s_waitcnt lgkmcnt(0)
	v_pk_add_f32 v[20:21], v[20:21], v[32:33]
	ds_bpermute_b32 v33, v72, v21
	ds_bpermute_b32 v32, v72, v20
	s_waitcnt lgkmcnt(0)
	v_pk_add_f32 v[20:21], v[20:21], v[32:33]
	ds_bpermute_b32 v33, v71, v21
	ds_bpermute_b32 v32, v71, v20
	s_waitcnt lgkmcnt(0)
	v_pk_add_f32 v[20:21], v[20:21], v[32:33]
	ds_bpermute_b32 v33, v67, v21
	ds_bpermute_b32 v32, v67, v20
	s_waitcnt lgkmcnt(0)
	v_pk_add_f32 v[20:21], v[20:21], v[32:33]
	ds_bpermute_b32 v33, v66, v21
	ds_bpermute_b32 v32, v66, v20
	s_waitcnt lgkmcnt(0)
	v_pk_add_f32 v[20:21], v[20:21], v[32:33]
	s_nop 0
	v_pk_fma_f32 v[20:21], v[20:21], s[78:79], v[16:17] op_sel_hi:[1,0,0]
	v_mov_b32_e32 v33, s1
	v_mul_f32_e32 v32, 0x4b800000, v21
	v_cmp_gt_f32_e64 s[6:7], s64, v21
	v_cmp_gt_f32_e32 vcc, s64, v20
	s_nop 0
	v_cndmask_b32_e64 v21, v21, v32, s[6:7]
	v_rsq_f32_e32 v21, v21
	s_nop 0
	v_mul_f32_e32 v32, 0x45800000, v21
	v_cndmask_b32_e64 v21, v21, v32, s[6:7]
	v_mul_f32_e32 v18, v18, v21
	v_mul_f32_e32 v18, v48, v18
	v_bfe_u32 v32, v18, 16, 1
	v_add3_u32 v18, v18, v32, s33
	v_mov_b32_e32 v82, v18
	v_mul_f32_e32 v18, v19, v21
	v_mul_f32_e32 v18, v68, v18
	v_bfe_u32 v19, v18, 16, 1
	v_add3_u32 v18, v18, v19, s33
	s_nop 1
	v_mov_b32_dpp v83, v82 quad_perm:[1,0,3,2] row_mask:0xf bank_mask:0xf
	v_mov_b32_dpp v84, v18 quad_perm:[1,0,3,2] row_mask:0xf bank_mask:0xf
	v_perm_b32 v85, v83, v82, s98
	v_perm_b32 v86, v18, v84, s98
	v_cndmask_b32_e64 v85, v85, v86, s[100:101]
	v_lshl_add_u64 v[88:89], v[76:77], 0, v[90:91]
	global_store_dword v[88:89], v85, off
	v_mul_f32_e32 v18, v35, v21
	v_mul_f32_e32 v18, v70, v18
	v_bfe_u32 v19, v18, 16, 1
	v_add3_u32 v18, v18, v19, s33
	v_mov_b32_e32 v82, v18
	v_mul_f32_e32 v18, v34, v21
	v_mul_f32_e32 v18, v69, v18
	v_bfe_u32 v19, v18, 16, 1
	v_add3_u32 v18, v18, v19, s33
	s_nop 1
	v_mov_b32_dpp v83, v82 quad_perm:[1,0,3,2] row_mask:0xf bank_mask:0xf
	v_mov_b32_dpp v84, v18 quad_perm:[1,0,3,2] row_mask:0xf bank_mask:0xf
	v_perm_b32 v85, v83, v82, s98
	v_perm_b32 v86, v18, v84, s98
	v_cndmask_b32_e64 v85, v85, v86, s[100:101]
	v_lshl_add_u64 v[88:89], v[76:77], 0, v[90:91]
	global_store_dword v[88:89], v85, off offset:128
	v_mul_f32_e32 v18, 0x4b800000, v20
	v_cndmask_b32_e32 v18, v20, v18, vcc
	v_rsq_f32_e32 v18, v18
	v_or_b32_e32 v32, 10, v64
	v_lshlrev_b64 v[32:33], 12, v[32:33]
	v_lshl_add_u64 v[32:33], s[12:13], 0, v[32:33]
	v_mul_f32_e32 v19, 0x45800000, v18
	v_cndmask_b32_e32 v20, v18, v19, vcc
	v_or_b32_e32 v18, 9, v64
	v_mov_b32_e32 v19, s1
	v_mul_f32_e32 v4, v4, v20
	v_lshlrev_b64 v[18:19], 12, v[18:19]
	v_mul_f32_e32 v4, v48, v4
	v_lshl_add_u64 v[18:19], s[12:13], 0, v[18:19]
	v_bfe_u32 v21, v4, 16, 1
	v_add3_u32 v4, v4, v21, s33
	v_lshl_add_u64 v[18:19], v[18:19], 0, v[80:81]
	v_mov_b32_e32 v82, v4
	v_mul_f32_e32 v4, v5, v20
	v_mul_f32_e32 v4, v68, v4
	v_bfe_u32 v5, v4, 16, 1
	v_mul_f32_e32 v1, v1, v20
	v_add3_u32 v4, v4, v5, s33
	v_mul_f32_e32 v1, v70, v1
	s_nop 1
	v_mov_b32_dpp v83, v82 quad_perm:[1,0,3,2] row_mask:0xf bank_mask:0xf
	v_mov_b32_dpp v84, v4 quad_perm:[1,0,3,2] row_mask:0xf bank_mask:0xf
	v_perm_b32 v85, v83, v82, s98
	v_perm_b32 v86, v4, v84, s98
	v_cndmask_b32_e64 v85, v85, v86, s[100:101]
	v_lshl_add_u64 v[88:89], v[18:19], 0, v[90:91]
	global_store_dword v[88:89], v85, off
	v_bfe_u32 v4, v1, 16, 1
	v_mul_f32_e32 v0, v0, v20
	v_add3_u32 v1, v1, v4, s33
	v_mul_f32_e32 v0, v69, v0
	v_mov_b32_e32 v82, v1
	v_bfe_u32 v1, v0, 16, 1
	v_add3_u32 v0, v0, v1, s33
	s_nop 1
	v_mov_b32_dpp v83, v82 quad_perm:[1,0,3,2] row_mask:0xf bank_mask:0xf
	v_mov_b32_dpp v84, v0 quad_perm:[1,0,3,2] row_mask:0xf bank_mask:0xf
	v_perm_b32 v85, v83, v82, s98
	v_perm_b32 v86, v0, v84, s98
	v_cndmask_b32_e64 v85, v85, v86, s[100:101]
	v_lshl_add_u64 v[88:89], v[18:19], 0, v[90:91]
	global_store_dword v[88:89], v85, off offset:128
	v_mov_b32_e32 v0, v6
	v_mov_b32_e32 v1, v22
	v_mov_b32_e32 v18, v54
	v_mov_b32_e32 v19, v38
	v_pk_mul_f32 v[0:1], v[0:1], v[2:3] op_sel_hi:[1,0]
	v_pk_mul_f32 v[18:19], v[18:19], v[2:3] op_sel_hi:[1,0]
	v_mov_b32_e32 v22, v7
	v_mov_b32_e32 v2, v3
	v_pk_mul_f32 v[6:7], v[22:23], v[2:3] op_sel_hi:[1,0]
	v_mov_b32_e32 v38, v55
	v_pk_mul_f32 v[4:5], v[0:1], v[0:1]
	v_pk_mul_f32 v[22:23], v[6:7], v[6:7]
	v_pk_mul_f32 v[2:3], v[38:39], v[2:3] op_sel_hi:[1,0]
	v_pk_mul_f32 v[20:21], v[18:19], v[18:19]
	v_pk_mul_f32 v[34:35], v[2:3], v[2:3]
	v_mov_b32_e32 v36, v22
	v_mov_b32_e32 v37, v4
	v_mov_b32_e32 v4, v23
	v_pk_add_f32 v[4:5], v[36:37], v[4:5]
	v_mov_b32_e32 v22, v35
	v_mov_b32_e32 v23, v21
	v_pk_add_f32 v[4:5], v[22:23], v[4:5]
	v_mov_b32_e32 v35, v20
	v_pk_add_f32 v[4:5], v[34:35], v[4:5]
	ds_bpermute_b32 v21, v73, v5
	ds_bpermute_b32 v20, v73, v4
	v_lshl_add_u64 v[32:33], v[32:33], 0, v[80:81]
	v_or_b32_e32 v22, 16, v64
	v_mov_b32_e32 v23, s1
	v_lshlrev_b64 v[22:23], 12, v[22:23]
	s_waitcnt lgkmcnt(0)
; DI unsigned f2bf(float f) { unsigned u = __builtin_bit_cast(unsigned, f); return (u + 0x7fffu + ((u >> 16) & 1u)) >> 16; }
; DI float shx(float v, int o, int lane) { return __int_as_float(__builtin_amdgcn_ds_bpermute((lane ^ o) << 2, __float_as_int(v))); }
; DI int crow(int i, int hh) { return (i & 3) + 8 * (i >> 2) + 4 * hh; }
; DI void attn_item(CArgs& a, LAS unsigned char* lds, int l, int b, int h, int qb, int tid_, int wave, int lane_) {
;     ...
;     for (int i = 0; i < 16; ++i) { const float inv = scr[crow(i, hh)]; float s = 0.f;
; #pragma unroll
;         for (int vt = 0; vt < 4; ++vt) { o[vt][i] *= inv; s += o[vt][i] * o[vt][i]; }
;         s += shx(s, 1, lane); s += shx(s, 2, lane); s += shx(s, 4, lane); s += shx(s, 8, lane); s += shx(s, 16, lane);
;         const float rs = rsqrtf(s * (1.f / 128.f) + EPS);
; #pragma unroll
;         for (int vt = 0; vt < 4; ++vt) { const int col = h * 128 + 32 * vt + r; mix[(trow0 + crow(i, hh)) * DM + 1024 + col] = (bf16_t)f2bf(o[vt][i] * rs * a.in[I_MIXG][l * DM + 1024 + col]); } }
	v_pk_add_f32 v[4:5], v[4:5], v[20:21]
	ds_bpermute_b32 v21, v72, v5
	ds_bpermute_b32 v20, v72, v4
	v_lshl_add_u64 v[22:23], s[12:13], 0, v[22:23]
	v_lshl_add_u64 v[22:23], v[22:23], 0, v[80:81]
	s_waitcnt lgkmcnt(0)
	v_pk_add_f32 v[4:5], v[4:5], v[20:21]
	ds_bpermute_b32 v21, v71, v5
	ds_bpermute_b32 v20, v71, v4
	s_waitcnt lgkmcnt(0)
	v_pk_add_f32 v[4:5], v[4:5], v[20:21]
	ds_bpermute_b32 v21, v67, v5
	ds_bpermute_b32 v20, v67, v4
	s_waitcnt lgkmcnt(0)
	v_pk_add_f32 v[4:5], v[4:5], v[20:21]
	ds_bpermute_b32 v21, v66, v5
	ds_bpermute_b32 v20, v66, v4
	s_waitcnt lgkmcnt(0)
	v_pk_add_f32 v[4:5], v[4:5], v[20:21]
	s_nop 0
	v_pk_fma_f32 v[4:5], v[4:5], s[78:79], v[16:17] op_sel_hi:[1,0,0]
	s_nop 0
	v_mul_f32_e32 v20, 0x4b800000, v5
	v_cmp_gt_f32_e64 s[6:7], s64, v5
	v_cmp_gt_f32_e32 vcc, s64, v4
	s_nop 0
	v_cndmask_b32_e64 v5, v5, v20, s[6:7]
	v_rsq_f32_e32 v5, v5
	s_nop 0
	v_mul_f32_e32 v20, 0x45800000, v5
	v_cndmask_b32_e64 v5, v5, v20, s[6:7]
	v_mul_f32_e32 v0, v0, v5
	v_mul_f32_e32 v0, v48, v0
	v_bfe_u32 v20, v0, 16, 1
	v_add3_u32 v0, v0, v20, s33
	v_mov_b32_e32 v82, v0
	v_mul_f32_e32 v0, v1, v5
	v_mul_f32_e32 v0, v68, v0
	v_bfe_u32 v1, v0, 16, 1
	v_add3_u32 v0, v0, v1, s33
	s_nop 1
	v_mov_b32_dpp v83, v82 quad_perm:[1,0,3,2] row_mask:0xf bank_mask:0xf
	v_mov_b32_dpp v84, v0 quad_perm:[1,0,3,2] row_mask:0xf bank_mask:0xf
	v_perm_b32 v85, v83, v82, s98
	v_perm_b32 v86, v0, v84, s98
	v_cndmask_b32_e64 v85, v85, v86, s[100:101]
	v_lshl_add_u64 v[88:89], v[32:33], 0, v[90:91]
	global_store_dword v[88:89], v85, off
	v_mul_f32_e32 v0, v19, v5
	v_mul_f32_e32 v0, v70, v0
	v_bfe_u32 v1, v0, 16, 1
	v_add3_u32 v0, v0, v1, s33
	v_mov_b32_e32 v82, v0
	v_mul_f32_e32 v0, v18, v5
	v_mul_f32_e32 v0, v69, v0
	v_bfe_u32 v1, v0, 16, 1
	v_add3_u32 v0, v0, v1, s33
	s_nop 1
	v_mov_b32_dpp v83, v82 quad_perm:[1,0,3,2] row_mask:0xf bank_mask:0xf
	v_mov_b32_dpp v84, v0 quad_perm:[1,0,3,2] row_mask:0xf bank_mask:0xf
	v_perm_b32 v85, v83, v82, s98
	v_perm_b32 v86, v0, v84, s98
	v_cndmask_b32_e64 v85, v85, v86, s[100:101]
	v_lshl_add_u64 v[88:89], v[32:33], 0, v[90:91]
	global_store_dword v[88:89], v85, off offset:128
	v_mul_f32_e32 v0, 0x4b800000, v4
	v_cndmask_b32_e32 v0, v4, v0, vcc
	v_rsq_f32_e32 v0, v0
	v_mov_b32_e32 v18, v56
	v_mov_b32_e32 v19, v40
	v_mov_b32_e32 v40, v57
	v_mul_f32_e32 v1, 0x45800000, v0
	v_cndmask_b32_e32 v4, v0, v1, vcc
	v_or_b32_e32 v0, 11, v64
	v_mov_b32_e32 v1, s1
	v_mul_f32_e32 v5, v6, v4
	v_lshlrev_b64 v[0:1], 12, v[0:1]
	v_mul_f32_e32 v5, v48, v5
	v_lshl_add_u64 v[0:1], s[12:13], 0, v[0:1]
	v_bfe_u32 v6, v5, 16, 1
	v_add3_u32 v5, v5, v6, s33
	v_lshl_add_u64 v[0:1], v[0:1], 0, v[80:81]
	v_mov_b32_e32 v82, v5
	v_mul_f32_e32 v5, v7, v4
	v_mul_f32_e32 v5, v68, v5
	v_bfe_u32 v6, v5, 16, 1
	v_mul_f32_e32 v3, v3, v4
	v_add3_u32 v5, v5, v6, s33
	v_mul_f32_e32 v3, v70, v3
	s_nop 1
	v_mov_b32_dpp v83, v82 quad_perm:[1,0,3,2] row_mask:0xf bank_mask:0xf
	v_mov_b32_dpp v84, v5 quad_perm:[1,0,3,2] row_mask:0xf bank_mask:0xf
	v_perm_b32 v85, v83, v82, s98
	v_perm_b32 v86, v5, v84, s98
	v_cndmask_b32_e64 v85, v85, v86, s[100:101]
	v_lshl_add_u64 v[88:89], v[0:1], 0, v[90:91]
	global_store_dword v[88:89], v85, off
	v_bfe_u32 v5, v3, 16, 1
	v_mul_f32_e32 v2, v2, v4
	v_add3_u32 v3, v3, v5, s33
	v_mul_f32_e32 v2, v69, v2
	v_mov_b32_e32 v82, v3
	v_bfe_u32 v3, v2, 16, 1
	v_add3_u32 v2, v2, v3, s33
	s_nop 1
	v_mov_b32_dpp v83, v82 quad_perm:[1,0,3,2] row_mask:0xf bank_mask:0xf
	v_mov_b32_dpp v84, v2 quad_perm:[1,0,3,2] row_mask:0xf bank_mask:0xf
	v_perm_b32 v85, v83, v82, s98
	v_perm_b32 v86, v2, v84, s98
	v_cndmask_b32_e64 v85, v85, v86, s[100:101]
	v_lshl_add_u64 v[88:89], v[0:1], 0, v[90:91]
	global_store_dword v[88:89], v85, off offset:128
	ds_read_b128 v[0:3], v74 offset:64
	v_mov_b32_e32 v4, v8
	v_mov_b32_e32 v5, v24
	v_mov_b32_e32 v24, v9
	s_waitcnt lgkmcnt(0)
	v_pk_mul_f32 v[4:5], v[4:5], v[0:1] op_sel_hi:[1,0]
	v_pk_mul_f32 v[8:9], v[24:25], v[0:1] op_sel:[0,1]
	v_pk_mul_f32 v[6:7], v[4:5], v[4:5]
	v_pk_mul_f32 v[18:19], v[18:19], v[0:1] op_sel_hi:[1,0]
	v_pk_mul_f32 v[24:25], v[8:9], v[8:9]
	v_pk_mul_f32 v[0:1], v[40:41], v[0:1] op_sel:[0,1]
	v_pk_mul_f32 v[20:21], v[18:19], v[18:19]
	v_pk_mul_f32 v[32:33], v[0:1], v[0:1]
	v_mov_b32_e32 v34, v24
	v_mov_b32_e32 v35, v6
	v_mov_b32_e32 v6, v25
	v_pk_add_f32 v[6:7], v[34:35], v[6:7]
	v_mov_b32_e32 v24, v33
	v_mov_b32_e32 v25, v21
	v_pk_add_f32 v[6:7], v[24:25], v[6:7]
	v_mov_b32_e32 v33, v20
	v_pk_add_f32 v[6:7], v[32:33], v[6:7]
	ds_bpermute_b32 v21, v73, v7
	ds_bpermute_b32 v20, v73, v6
	s_waitcnt lgkmcnt(0)
	v_pk_add_f32 v[6:7], v[6:7], v[20:21]
	ds_bpermute_b32 v21, v72, v7
	ds_bpermute_b32 v20, v72, v6
	s_waitcnt lgkmcnt(0)
	v_pk_add_f32 v[6:7], v[6:7], v[20:21]
	ds_bpermute_b32 v21, v71, v7
	ds_bpermute_b32 v20, v71, v6
	s_waitcnt lgkmcnt(0)
	v_pk_add_f32 v[6:7], v[6:7], v[20:21]
	ds_bpermute_b32 v21, v67, v7
	ds_bpermute_b32 v20, v67, v6
	s_waitcnt lgkmcnt(0)
	v_pk_add_f32 v[6:7], v[6:7], v[20:21]
	ds_bpermute_b32 v21, v66, v7
	ds_bpermute_b32 v20, v66, v6
	s_waitcnt lgkmcnt(0)
; DI unsigned f2bf(float f) { unsigned u = __builtin_bit_cast(unsigned, f); return (u + 0x7fffu + ((u >> 16) & 1u)) >> 16; }
; DI float shx(float v, int o, int lane) { return __int_as_float(__builtin_amdgcn_ds_bpermute((lane ^ o) << 2, __float_as_int(v))); }
; DI int crow(int i, int hh) { return (i & 3) + 8 * (i >> 2) + 4 * hh; }
; DI void attn_item(CArgs& a, LAS unsigned char* lds, int l, int b, int h, int qb, int tid_, int wave, int lane_) {
;     ...
;     for (int i = 0; i < 16; ++i) { const float inv = scr[crow(i, hh)]; float s = 0.f;
; #pragma unroll
;         for (int vt = 0; vt < 4; ++vt) { o[vt][i] *= inv; s += o[vt][i] * o[vt][i]; }
;         s += shx(s, 1, lane); s += shx(s, 2, lane); s += shx(s, 4, lane); s += shx(s, 8, lane); s += shx(s, 16, lane);
;         const float rs = rsqrtf(s * (1.f / 128.f) + EPS);
; #pragma unroll
;         for (int vt = 0; vt < 4; ++vt) { const int col = h * 128 + 32 * vt + r; mix[(trow0 + crow(i, hh)) * DM + 1024 + col] = (bf16_t)f2bf(o[vt][i] * rs * a.in[I_MIXG][l * DM + 1024 + col]); } }
	v_pk_add_f32 v[6:7], v[6:7], v[20:21]
	s_nop 0
	v_pk_fma_f32 v[6:7], v[6:7], s[78:79], v[16:17] op_sel_hi:[1,0,0]
	s_nop 0
	v_mul_f32_e32 v20, 0x4b800000, v7
	v_cmp_gt_f32_e64 s[6:7], s64, v7
	v_cmp_gt_f32_e32 vcc, s64, v6
	s_nop 0
	v_cndmask_b32_e64 v7, v7, v20, s[6:7]
	v_rsq_f32_e32 v7, v7
	s_nop 0
	v_mul_f32_e32 v20, 0x45800000, v7
	v_cndmask_b32_e64 v7, v7, v20, s[6:7]
	v_mul_f32_e32 v4, v4, v7
	v_mul_f32_e32 v4, v48, v4
	v_bfe_u32 v20, v4, 16, 1
	v_add3_u32 v4, v4, v20, s33
	v_mov_b32_e32 v82, v4
	v_mul_f32_e32 v4, v5, v7
	v_mul_f32_e32 v4, v68, v4
	v_bfe_u32 v5, v4, 16, 1
	v_add3_u32 v4, v4, v5, s33
	s_nop 1
	v_mov_b32_dpp v83, v82 quad_perm:[1,0,3,2] row_mask:0xf bank_mask:0xf
	v_mov_b32_dpp v84, v4 quad_perm:[1,0,3,2] row_mask:0xf bank_mask:0xf
	v_perm_b32 v85, v83, v82, s98
	v_perm_b32 v86, v4, v84, s98
	v_cndmask_b32_e64 v85, v85, v86, s[100:101]
	v_lshl_add_u64 v[88:89], v[22:23], 0, v[90:91]
	global_store_dword v[88:89], v85, off
	v_mul_f32_e32 v4, v19, v7
	v_mul_f32_e32 v4, v70, v4
	v_bfe_u32 v5, v4, 16, 1
	v_add3_u32 v4, v4, v5, s33
	v_mov_b32_e32 v82, v4
	v_mul_f32_e32 v4, v18, v7
	v_mul_f32_e32 v4, v69, v4
	v_bfe_u32 v5, v4, 16, 1
	v_add3_u32 v4, v4, v5, s33
	s_nop 1
	v_mov_b32_dpp v83, v82 quad_perm:[1,0,3,2] row_mask:0xf bank_mask:0xf
	v_mov_b32_dpp v84, v4 quad_perm:[1,0,3,2] row_mask:0xf bank_mask:0xf
	v_perm_b32 v85, v83, v82, s98
	v_perm_b32 v86, v4, v84, s98
	v_cndmask_b32_e64 v85, v85, v86, s[100:101]
	v_lshl_add_u64 v[88:89], v[22:23], 0, v[90:91]
	global_store_dword v[88:89], v85, off offset:128
	v_mul_f32_e32 v4, 0x4b800000, v6
	v_cndmask_b32_e32 v4, v6, v4, vcc
	v_rsq_f32_e32 v4, v4
	v_or_b32_e32 v18, 18, v64
	v_mov_b32_e32 v19, s1
	v_lshlrev_b64 v[18:19], 12, v[18:19]
	v_mul_f32_e32 v5, 0x45800000, v4
	v_cndmask_b32_e32 v6, v4, v5, vcc
	v_or_b32_e32 v4, 17, v64
	v_mov_b32_e32 v5, s1
	v_mul_f32_e32 v7, v8, v6
	v_lshlrev_b64 v[4:5], 12, v[4:5]
	v_mul_f32_e32 v7, v48, v7
	v_lshl_add_u64 v[4:5], s[12:13], 0, v[4:5]
	v_bfe_u32 v8, v7, 16, 1
	v_add3_u32 v7, v7, v8, s33
	v_lshl_add_u64 v[4:5], v[4:5], 0, v[80:81]
	v_mov_b32_e32 v82, v7
	v_mul_f32_e32 v7, v9, v6
	v_mul_f32_e32 v7, v68, v7
	v_bfe_u32 v8, v7, 16, 1
	v_mul_f32_e32 v1, v1, v6
	v_add3_u32 v7, v7, v8, s33
	v_mul_f32_e32 v1, v70, v1
	s_nop 1
	v_mov_b32_dpp v83, v82 quad_perm:[1,0,3,2] row_mask:0xf bank_mask:0xf
	v_mov_b32_dpp v84, v7 quad_perm:[1,0,3,2] row_mask:0xf bank_mask:0xf
	v_perm_b32 v85, v83, v82, s98
	v_perm_b32 v86, v7, v84, s98
	v_cndmask_b32_e64 v85, v85, v86, s[100:101]
	v_lshl_add_u64 v[88:89], v[4:5], 0, v[90:91]
	global_store_dword v[88:89], v85, off
	v_bfe_u32 v7, v1, 16, 1
	v_mul_f32_e32 v0, v0, v6
	v_add3_u32 v1, v1, v7, s33
	v_mul_f32_e32 v0, v69, v0
	v_mov_b32_e32 v82, v1
	v_bfe_u32 v1, v0, 16, 1
	v_add3_u32 v0, v0, v1, s33
	s_nop 1
	v_mov_b32_dpp v83, v82 quad_perm:[1,0,3,2] row_mask:0xf bank_mask:0xf
	v_mov_b32_dpp v84, v0 quad_perm:[1,0,3,2] row_mask:0xf bank_mask:0xf
	v_perm_b32 v85, v83, v82, s98
	v_perm_b32 v86, v0, v84, s98
	v_cndmask_b32_e64 v85, v85, v86, s[100:101]
	v_lshl_add_u64 v[88:89], v[4:5], 0, v[90:91]
	global_store_dword v[88:89], v85, off offset:128
	v_mov_b32_e32 v0, v10
	v_mov_b32_e32 v1, v26
	v_mov_b32_e32 v6, v58
	v_mov_b32_e32 v7, v42
	v_pk_mul_f32 v[0:1], v[0:1], v[2:3] op_sel_hi:[1,0]
	v_pk_mul_f32 v[6:7], v[6:7], v[2:3] op_sel_hi:[1,0]
	v_mov_b32_e32 v26, v11
	v_mov_b32_e32 v2, v3
	v_pk_mul_f32 v[10:11], v[26:27], v[2:3] op_sel_hi:[1,0]
	v_mov_b32_e32 v42, v59
	v_pk_mul_f32 v[4:5], v[0:1], v[0:1]
	v_pk_mul_f32 v[20:21], v[10:11], v[10:11]
	v_pk_mul_f32 v[2:3], v[42:43], v[2:3] op_sel_hi:[1,0]
	v_pk_mul_f32 v[8:9], v[6:7], v[6:7]
	v_pk_mul_f32 v[22:23], v[2:3], v[2:3]
	v_mov_b32_e32 v24, v20
	v_mov_b32_e32 v25, v4
	v_mov_b32_e32 v4, v21
	v_pk_add_f32 v[4:5], v[24:25], v[4:5]
	v_mov_b32_e32 v20, v23
	v_mov_b32_e32 v21, v9
	v_pk_add_f32 v[4:5], v[20:21], v[4:5]
	v_mov_b32_e32 v23, v8
	v_pk_add_f32 v[4:5], v[22:23], v[4:5]
	ds_bpermute_b32 v9, v73, v5
	ds_bpermute_b32 v8, v73, v4
	v_lshl_add_u64 v[18:19], s[12:13], 0, v[18:19]
	v_lshl_add_u64 v[18:19], v[18:19], 0, v[80:81]
	s_waitcnt lgkmcnt(0)
	v_pk_add_f32 v[4:5], v[4:5], v[8:9]
	ds_bpermute_b32 v9, v72, v5
	ds_bpermute_b32 v8, v72, v4
	s_waitcnt lgkmcnt(0)
	v_pk_add_f32 v[4:5], v[4:5], v[8:9]
	ds_bpermute_b32 v9, v71, v5
	ds_bpermute_b32 v8, v71, v4
	s_waitcnt lgkmcnt(0)
	v_pk_add_f32 v[4:5], v[4:5], v[8:9]
	ds_bpermute_b32 v9, v67, v5
	ds_bpermute_b32 v8, v67, v4
	s_waitcnt lgkmcnt(0)
	v_pk_add_f32 v[4:5], v[4:5], v[8:9]
	ds_bpermute_b32 v9, v66, v5
	ds_bpermute_b32 v8, v66, v4
	s_waitcnt lgkmcnt(0)
; DI unsigned f2bf(float f) { unsigned u = __builtin_bit_cast(unsigned, f); return (u + 0x7fffu + ((u >> 16) & 1u)) >> 16; }
; DI float shx(float v, int o, int lane) { return __int_as_float(__builtin_amdgcn_ds_bpermute((lane ^ o) << 2, __float_as_int(v))); }
; DI int crow(int i, int hh) { return (i & 3) + 8 * (i >> 2) + 4 * hh; }
; DI void attn_item(CArgs& a, LAS unsigned char* lds, int l, int b, int h, int qb, int tid_, int wave, int lane_) {
;     ...
;     for (int i = 0; i < 16; ++i) { const float inv = scr[crow(i, hh)]; float s = 0.f;
; #pragma unroll
;         for (int vt = 0; vt < 4; ++vt) { o[vt][i] *= inv; s += o[vt][i] * o[vt][i]; }
;         s += shx(s, 1, lane); s += shx(s, 2, lane); s += shx(s, 4, lane); s += shx(s, 8, lane); s += shx(s, 16, lane);
;         const float rs = rsqrtf(s * (1.f / 128.f) + EPS);
; #pragma unroll
;         for (int vt = 0; vt < 4; ++vt) { const int col = h * 128 + 32 * vt + r; mix[(trow0 + crow(i, hh)) * DM + 1024 + col] = (bf16_t)f2bf(o[vt][i] * rs * a.in[I_MIXG][l * DM + 1024 + col]); } }
	v_pk_add_f32 v[4:5], v[4:5], v[8:9]
	s_nop 0
	v_pk_fma_f32 v[4:5], v[4:5], s[78:79], v[16:17] op_sel_hi:[1,0,0]
	v_mov_b32_e32 v9, v44
	v_mul_f32_e32 v8, 0x4b800000, v5
	v_cmp_gt_f32_e64 s[6:7], s64, v5
	v_cmp_gt_f32_e32 vcc, s64, v4
	v_mov_b32_e32 v44, v61
	v_cndmask_b32_e64 v5, v5, v8, s[6:7]
	v_rsq_f32_e32 v5, v5
	s_nop 0
	v_mul_f32_e32 v8, 0x45800000, v5
	v_cndmask_b32_e64 v5, v5, v8, s[6:7]
	v_mul_f32_e32 v0, v0, v5
	v_mul_f32_e32 v0, v48, v0
	v_bfe_u32 v8, v0, 16, 1
	v_add3_u32 v0, v0, v8, s33
	v_mov_b32_e32 v82, v0
	v_mul_f32_e32 v0, v1, v5
	v_mul_f32_e32 v0, v68, v0
	v_bfe_u32 v1, v0, 16, 1
	v_add3_u32 v0, v0, v1, s33
	s_nop 1
	v_mov_b32_dpp v83, v82 quad_perm:[1,0,3,2] row_mask:0xf bank_mask:0xf
	v_mov_b32_dpp v84, v0 quad_perm:[1,0,3,2] row_mask:0xf bank_mask:0xf
	v_perm_b32 v85, v83, v82, s98
	v_perm_b32 v86, v0, v84, s98
	v_cndmask_b32_e64 v85, v85, v86, s[100:101]
	v_lshl_add_u64 v[88:89], v[18:19], 0, v[90:91]
	global_store_dword v[88:89], v85, off
	v_mul_f32_e32 v0, v7, v5
	v_mul_f32_e32 v0, v70, v0
	v_bfe_u32 v1, v0, 16, 1
	v_add3_u32 v0, v0, v1, s33
	v_mov_b32_e32 v82, v0
	v_mul_f32_e32 v0, v6, v5
	v_mul_f32_e32 v0, v69, v0
	v_bfe_u32 v1, v0, 16, 1
	v_add3_u32 v0, v0, v1, s33
	s_nop 1
	v_mov_b32_dpp v83, v82 quad_perm:[1,0,3,2] row_mask:0xf bank_mask:0xf
	v_mov_b32_dpp v84, v0 quad_perm:[1,0,3,2] row_mask:0xf bank_mask:0xf
	v_perm_b32 v85, v83, v82, s98
	v_perm_b32 v86, v0, v84, s98
	v_cndmask_b32_e64 v85, v85, v86, s[100:101]
	v_lshl_add_u64 v[88:89], v[18:19], 0, v[90:91]
	global_store_dword v[88:89], v85, off offset:128
	v_mul_f32_e32 v0, 0x4b800000, v4
	v_cndmask_b32_e32 v0, v4, v0, vcc
	v_rsq_f32_e32 v0, v0
	v_mov_b32_e32 v8, v60
	v_or_b32_e32 v18, 24, v64
	v_mov_b32_e32 v19, s1
	v_mul_f32_e32 v1, 0x45800000, v0
	v_cndmask_b32_e32 v4, v0, v1, vcc
	v_or_b32_e32 v0, 19, v64
	v_mov_b32_e32 v1, s1
	v_mul_f32_e32 v5, v10, v4
	v_lshlrev_b64 v[0:1], 12, v[0:1]
	v_mul_f32_e32 v5, v48, v5
	v_lshl_add_u64 v[0:1], s[12:13], 0, v[0:1]
	v_bfe_u32 v6, v5, 16, 1
	v_add3_u32 v5, v5, v6, s33
	v_lshl_add_u64 v[0:1], v[0:1], 0, v[80:81]
	v_mov_b32_e32 v82, v5
	v_mul_f32_e32 v5, v11, v4
	v_mul_f32_e32 v5, v68, v5
	v_bfe_u32 v6, v5, 16, 1
	v_mul_f32_e32 v3, v3, v4
	v_add3_u32 v5, v5, v6, s33
	v_mul_f32_e32 v3, v70, v3
	s_nop 1
	v_mov_b32_dpp v83, v82 quad_perm:[1,0,3,2] row_mask:0xf bank_mask:0xf
	v_mov_b32_dpp v84, v5 quad_perm:[1,0,3,2] row_mask:0xf bank_mask:0xf
	v_perm_b32 v85, v83, v82, s98
	v_perm_b32 v86, v5, v84, s98
	v_cndmask_b32_e64 v85, v85, v86, s[100:101]
	v_lshl_add_u64 v[88:89], v[0:1], 0, v[90:91]
	global_store_dword v[88:89], v85, off
	v_bfe_u32 v5, v3, 16, 1
	v_mul_f32_e32 v2, v2, v4
	v_add3_u32 v3, v3, v5, s33
	v_mul_f32_e32 v2, v69, v2
	v_mov_b32_e32 v82, v3
	v_bfe_u32 v3, v2, 16, 1
	v_add3_u32 v2, v2, v3, s33
	s_nop 1
	v_mov_b32_dpp v83, v82 quad_perm:[1,0,3,2] row_mask:0xf bank_mask:0xf
	v_mov_b32_dpp v84, v2 quad_perm:[1,0,3,2] row_mask:0xf bank_mask:0xf
	v_perm_b32 v85, v83, v82, s98
	v_perm_b32 v86, v2, v84, s98
	v_cndmask_b32_e64 v85, v85, v86, s[100:101]
	v_lshl_add_u64 v[88:89], v[0:1], 0, v[90:91]
	global_store_dword v[88:89], v85, off offset:128
	ds_read_b128 v[0:3], v74 offset:96
	v_mov_b32_e32 v4, v12
	v_mov_b32_e32 v5, v28
	v_mov_b32_e32 v28, v13
	v_lshlrev_b64 v[18:19], 12, v[18:19]
	s_waitcnt lgkmcnt(0)
	v_pk_mul_f32 v[4:5], v[4:5], v[0:1] op_sel_hi:[1,0]
	v_pk_mul_f32 v[12:13], v[28:29], v[0:1] op_sel:[0,1]
	v_pk_mul_f32 v[6:7], v[4:5], v[4:5]
	v_pk_mul_f32 v[8:9], v[8:9], v[0:1] op_sel_hi:[1,0]
	v_pk_mul_f32 v[20:21], v[12:13], v[12:13]
	v_pk_mul_f32 v[0:1], v[44:45], v[0:1] op_sel:[0,1]
	v_pk_mul_f32 v[10:11], v[8:9], v[8:9]
	v_pk_mul_f32 v[22:23], v[0:1], v[0:1]
	v_mov_b32_e32 v24, v20
	v_mov_b32_e32 v25, v6
	v_mov_b32_e32 v6, v21
	v_pk_add_f32 v[6:7], v[24:25], v[6:7]
	v_mov_b32_e32 v20, v23
	v_mov_b32_e32 v21, v11
	v_pk_add_f32 v[6:7], v[20:21], v[6:7]
	v_mov_b32_e32 v23, v10
	v_pk_add_f32 v[6:7], v[22:23], v[6:7]
	ds_bpermute_b32 v11, v73, v7
	ds_bpermute_b32 v10, v73, v6
	v_lshl_add_u64 v[18:19], s[12:13], 0, v[18:19]
	v_lshl_add_u64 v[18:19], v[18:19], 0, v[80:81]
	s_waitcnt lgkmcnt(0)
	v_pk_add_f32 v[6:7], v[6:7], v[10:11]
	ds_bpermute_b32 v11, v72, v7
	ds_bpermute_b32 v10, v72, v6
	s_waitcnt lgkmcnt(0)
	v_pk_add_f32 v[6:7], v[6:7], v[10:11]
	ds_bpermute_b32 v11, v71, v7
	ds_bpermute_b32 v10, v71, v6
	s_waitcnt lgkmcnt(0)
	v_pk_add_f32 v[6:7], v[6:7], v[10:11]
	ds_bpermute_b32 v11, v67, v7
	ds_bpermute_b32 v10, v67, v6
	s_waitcnt lgkmcnt(0)
	v_pk_add_f32 v[6:7], v[6:7], v[10:11]
	ds_bpermute_b32 v11, v66, v7
	ds_bpermute_b32 v10, v66, v6
	s_waitcnt lgkmcnt(0)
; DI unsigned f2bf(float f) { unsigned u = __builtin_bit_cast(unsigned, f); return (u + 0x7fffu + ((u >> 16) & 1u)) >> 16; }
; DI float shx(float v, int o, int lane) { return __int_as_float(__builtin_amdgcn_ds_bpermute((lane ^ o) << 2, __float_as_int(v))); }
; DI int crow(int i, int hh) { return (i & 3) + 8 * (i >> 2) + 4 * hh; }
; DI void attn_item(CArgs& a, LAS unsigned char* lds, int l, int b, int h, int qb, int tid_, int wave, int lane_) {
;     ...
;     for (int i = 0; i < 16; ++i) { const float inv = scr[crow(i, hh)]; float s = 0.f;
; #pragma unroll
;         for (int vt = 0; vt < 4; ++vt) { o[vt][i] *= inv; s += o[vt][i] * o[vt][i]; }
;         s += shx(s, 1, lane); s += shx(s, 2, lane); s += shx(s, 4, lane); s += shx(s, 8, lane); s += shx(s, 16, lane);
;         const float rs = rsqrtf(s * (1.f / 128.f) + EPS);
; #pragma unroll
;         for (int vt = 0; vt < 4; ++vt) { const int col = h * 128 + 32 * vt + r; mix[(trow0 + crow(i, hh)) * DM + 1024 + col] = (bf16_t)f2bf(o[vt][i] * rs * a.in[I_MIXG][l * DM + 1024 + col]); } }
	v_pk_add_f32 v[6:7], v[6:7], v[10:11]
	s_nop 0
	v_pk_fma_f32 v[6:7], v[6:7], s[78:79], v[16:17] op_sel_hi:[1,0,0]
	v_mov_b32_e32 v11, s1
	v_mul_f32_e32 v10, 0x4b800000, v7
	v_cmp_gt_f32_e64 s[6:7], s64, v7
	v_cmp_gt_f32_e32 vcc, s64, v6
	s_nop 0
	v_cndmask_b32_e64 v7, v7, v10, s[6:7]
	v_rsq_f32_e32 v7, v7
	s_nop 0
	v_mul_f32_e32 v10, 0x45800000, v7
	v_cndmask_b32_e64 v7, v7, v10, s[6:7]
	v_mul_f32_e32 v4, v4, v7
	v_mul_f32_e32 v4, v48, v4
	v_bfe_u32 v10, v4, 16, 1
	v_add3_u32 v4, v4, v10, s33
	v_mov_b32_e32 v82, v4
	v_mul_f32_e32 v4, v5, v7
	v_mul_f32_e32 v4, v68, v4
	v_bfe_u32 v5, v4, 16, 1
	v_add3_u32 v4, v4, v5, s33
	s_nop 1
	v_mov_b32_dpp v83, v82 quad_perm:[1,0,3,2] row_mask:0xf bank_mask:0xf
	v_mov_b32_dpp v84, v4 quad_perm:[1,0,3,2] row_mask:0xf bank_mask:0xf
	v_perm_b32 v85, v83, v82, s98
	v_perm_b32 v86, v4, v84, s98
	v_cndmask_b32_e64 v85, v85, v86, s[100:101]
	v_lshl_add_u64 v[88:89], v[18:19], 0, v[90:91]
	global_store_dword v[88:89], v85, off
	v_mul_f32_e32 v4, v9, v7
	v_mul_f32_e32 v4, v70, v4
	v_bfe_u32 v5, v4, 16, 1
	v_add3_u32 v4, v4, v5, s33
	v_mov_b32_e32 v82, v4
	v_mul_f32_e32 v4, v8, v7
	v_mul_f32_e32 v4, v69, v4
	v_bfe_u32 v5, v4, 16, 1
	v_add3_u32 v4, v4, v5, s33
	s_nop 1
	v_mov_b32_dpp v83, v82 quad_perm:[1,0,3,2] row_mask:0xf bank_mask:0xf
	v_mov_b32_dpp v84, v4 quad_perm:[1,0,3,2] row_mask:0xf bank_mask:0xf
	v_perm_b32 v85, v83, v82, s98
	v_perm_b32 v86, v4, v84, s98
	v_cndmask_b32_e64 v85, v85, v86, s[100:101]
	v_lshl_add_u64 v[88:89], v[18:19], 0, v[90:91]
	global_store_dword v[88:89], v85, off offset:128
	v_mul_f32_e32 v4, 0x4b800000, v6
	v_cndmask_b32_e32 v4, v6, v4, vcc
	v_rsq_f32_e32 v4, v4
	v_or_b32_e32 v10, 26, v64
	v_lshlrev_b64 v[10:11], 12, v[10:11]
	v_lshl_add_u64 v[10:11], s[12:13], 0, v[10:11]
	v_mul_f32_e32 v5, 0x45800000, v4
	v_cndmask_b32_e32 v6, v4, v5, vcc
	v_or_b32_e32 v4, 25, v64
	v_mov_b32_e32 v5, s1
	v_mul_f32_e32 v7, v12, v6
	v_lshlrev_b64 v[4:5], 12, v[4:5]
	v_mul_f32_e32 v7, v48, v7
	v_lshl_add_u64 v[4:5], s[12:13], 0, v[4:5]
	v_bfe_u32 v8, v7, 16, 1
	v_add3_u32 v7, v7, v8, s33
	v_lshl_add_u64 v[4:5], v[4:5], 0, v[80:81]
	v_mov_b32_e32 v82, v7
	v_mul_f32_e32 v7, v13, v6
	v_mul_f32_e32 v7, v68, v7
	v_bfe_u32 v8, v7, 16, 1
	v_mul_f32_e32 v1, v1, v6
	v_add3_u32 v7, v7, v8, s33
	v_mul_f32_e32 v1, v70, v1
	s_nop 1
	v_mov_b32_dpp v83, v82 quad_perm:[1,0,3,2] row_mask:0xf bank_mask:0xf
	v_mov_b32_dpp v84, v7 quad_perm:[1,0,3,2] row_mask:0xf bank_mask:0xf
	v_perm_b32 v85, v83, v82, s98
	v_perm_b32 v86, v7, v84, s98
	v_cndmask_b32_e64 v85, v85, v86, s[100:101]
	v_lshl_add_u64 v[88:89], v[4:5], 0, v[90:91]
	global_store_dword v[88:89], v85, off
	v_bfe_u32 v7, v1, 16, 1
	v_mul_f32_e32 v0, v0, v6
	v_add3_u32 v1, v1, v7, s33
	v_mul_f32_e32 v0, v69, v0
	v_mov_b32_e32 v82, v1
	v_bfe_u32 v1, v0, 16, 1
	v_add3_u32 v0, v0, v1, s33
	s_nop 1
	v_mov_b32_dpp v83, v82 quad_perm:[1,0,3,2] row_mask:0xf bank_mask:0xf
	v_mov_b32_dpp v84, v0 quad_perm:[1,0,3,2] row_mask:0xf bank_mask:0xf
	v_perm_b32 v85, v83, v82, s98
	v_perm_b32 v86, v0, v84, s98
	v_cndmask_b32_e64 v85, v85, v86, s[100:101]
	v_lshl_add_u64 v[88:89], v[4:5], 0, v[90:91]
	global_store_dword v[88:89], v85, off offset:128
	v_mov_b32_e32 v0, v14
	v_mov_b32_e32 v1, v30
	v_mov_b32_e32 v6, v62
	v_mov_b32_e32 v7, v46
	v_pk_mul_f32 v[0:1], v[0:1], v[2:3] op_sel_hi:[1,0]
	v_pk_mul_f32 v[6:7], v[6:7], v[2:3] op_sel_hi:[1,0]
	v_mov_b32_e32 v30, v15
	v_mov_b32_e32 v2, v3
	v_pk_mul_f32 v[12:13], v[30:31], v[2:3] op_sel_hi:[1,0]
	v_mov_b32_e32 v46, v63
	v_pk_mul_f32 v[4:5], v[0:1], v[0:1]
	v_pk_mul_f32 v[14:15], v[12:13], v[12:13]
	v_pk_mul_f32 v[2:3], v[46:47], v[2:3] op_sel_hi:[1,0]
	v_pk_mul_f32 v[8:9], v[6:7], v[6:7]
	v_pk_mul_f32 v[18:19], v[2:3], v[2:3]
	v_mov_b32_e32 v20, v14
	v_mov_b32_e32 v21, v4
	v_mov_b32_e32 v4, v15
	v_pk_add_f32 v[4:5], v[20:21], v[4:5]
	v_mov_b32_e32 v14, v19
	v_mov_b32_e32 v15, v9
	v_pk_add_f32 v[4:5], v[14:15], v[4:5]
	v_mov_b32_e32 v19, v8
	v_pk_add_f32 v[4:5], v[18:19], v[4:5]
	ds_bpermute_b32 v9, v73, v5
	ds_bpermute_b32 v8, v73, v4
	v_lshl_add_u64 v[10:11], v[10:11], 0, v[80:81]
	v_or_b32_e32 v64, 27, v64
	s_waitcnt lgkmcnt(0)
; DI unsigned f2bf(float f) { unsigned u = __builtin_bit_cast(unsigned, f); return (u + 0x7fffu + ((u >> 16) & 1u)) >> 16; }
; DI float shx(float v, int o, int lane) { return __int_as_float(__builtin_amdgcn_ds_bpermute((lane ^ o) << 2, __float_as_int(v))); }
; DI int crow(int i, int hh) { return (i & 3) + 8 * (i >> 2) + 4 * hh; }
; DI void attn_item(CArgs& a, LAS unsigned char* lds, int l, int b, int h, int qb, int tid_, int wave, int lane_) {
;     ...
;     for (int i = 0; i < 16; ++i) { const float inv = scr[crow(i, hh)]; float s = 0.f;
; #pragma unroll
;         for (int vt = 0; vt < 4; ++vt) { o[vt][i] *= inv; s += o[vt][i] * o[vt][i]; }
;         s += shx(s, 1, lane); s += shx(s, 2, lane); s += shx(s, 4, lane); s += shx(s, 8, lane); s += shx(s, 16, lane);
;         const float rs = rsqrtf(s * (1.f / 128.f) + EPS);
; #pragma unroll
;         for (int vt = 0; vt < 4; ++vt) { const int col = h * 128 + 32 * vt + r; mix[(trow0 + crow(i, hh)) * DM + 1024 + col] = (bf16_t)f2bf(o[vt][i] * rs * a.in[I_MIXG][l * DM + 1024 + col]); } }
	v_pk_add_f32 v[4:5], v[4:5], v[8:9]
	ds_bpermute_b32 v9, v72, v5
	ds_bpermute_b32 v8, v72, v4
	s_waitcnt lgkmcnt(0)
	v_pk_add_f32 v[4:5], v[4:5], v[8:9]
	ds_bpermute_b32 v9, v71, v5
	ds_bpermute_b32 v8, v71, v4
	s_waitcnt lgkmcnt(0)
	v_pk_add_f32 v[4:5], v[4:5], v[8:9]
	ds_bpermute_b32 v9, v67, v5
	ds_bpermute_b32 v8, v67, v4
	s_waitcnt lgkmcnt(0)
	v_pk_add_f32 v[4:5], v[4:5], v[8:9]
	ds_bpermute_b32 v9, v66, v5
	ds_bpermute_b32 v8, v66, v4
	s_waitcnt lgkmcnt(0)
	v_pk_add_f32 v[4:5], v[4:5], v[8:9]
	s_nop 0
	v_pk_fma_f32 v[4:5], v[4:5], s[78:79], v[16:17] op_sel_hi:[1,0,0]
	s_nop 0
	v_mul_f32_e32 v8, 0x4b800000, v5
	v_cmp_gt_f32_e64 s[6:7], s64, v5
	v_cmp_gt_f32_e32 vcc, s64, v4
	s_nop 0
	v_cndmask_b32_e64 v5, v5, v8, s[6:7]
	v_rsq_f32_e32 v5, v5
	s_nop 0
	v_mul_f32_e32 v8, 0x45800000, v5
	v_cndmask_b32_e64 v5, v5, v8, s[6:7]
	v_mul_f32_e32 v0, v0, v5
	v_mul_f32_e32 v0, v48, v0
	v_bfe_u32 v8, v0, 16, 1
	v_add3_u32 v0, v0, v8, s33
	v_mov_b32_e32 v82, v0
	v_mul_f32_e32 v0, v1, v5
	v_mul_f32_e32 v0, v68, v0
	v_bfe_u32 v1, v0, 16, 1
	v_add3_u32 v0, v0, v1, s33
	s_nop 1
	v_mov_b32_dpp v83, v82 quad_perm:[1,0,3,2] row_mask:0xf bank_mask:0xf
	v_mov_b32_dpp v84, v0 quad_perm:[1,0,3,2] row_mask:0xf bank_mask:0xf
	v_perm_b32 v85, v83, v82, s98
	v_perm_b32 v86, v0, v84, s98
	v_cndmask_b32_e64 v85, v85, v86, s[100:101]
	v_lshl_add_u64 v[88:89], v[10:11], 0, v[90:91]
	global_store_dword v[88:89], v85, off
	v_mul_f32_e32 v0, v7, v5
	v_mul_f32_e32 v0, v70, v0
	v_bfe_u32 v1, v0, 16, 1
	v_add3_u32 v0, v0, v1, s33
	v_mov_b32_e32 v82, v0
	v_mul_f32_e32 v0, v6, v5
	v_mul_f32_e32 v0, v69, v0
	v_bfe_u32 v1, v0, 16, 1
	v_add3_u32 v0, v0, v1, s33
	s_nop 1
	v_mov_b32_dpp v83, v82 quad_perm:[1,0,3,2] row_mask:0xf bank_mask:0xf
	v_mov_b32_dpp v84, v0 quad_perm:[1,0,3,2] row_mask:0xf bank_mask:0xf
	v_perm_b32 v85, v83, v82, s98
	v_perm_b32 v86, v0, v84, s98
	v_cndmask_b32_e64 v85, v85, v86, s[100:101]
	v_lshl_add_u64 v[88:89], v[10:11], 0, v[90:91]
	global_store_dword v[88:89], v85, off offset:128
	v_mul_f32_e32 v0, 0x4b800000, v4
	v_cndmask_b32_e32 v0, v4, v0, vcc
	v_rsq_f32_e32 v0, v0
	s_nop 0
	v_mul_f32_e32 v1, 0x45800000, v0
	v_cndmask_b32_e32 v4, v0, v1, vcc
	v_mul_f32_e32 v5, v12, v4
	v_lshlrev_b64 v[0:1], 12, v[64:65]
	v_mul_f32_e32 v5, v48, v5
	v_lshl_add_u64 v[0:1], s[12:13], 0, v[0:1]
	v_bfe_u32 v6, v5, 16, 1
	v_add3_u32 v5, v5, v6, s33
	v_lshl_add_u64 v[0:1], v[0:1], 0, v[80:81]
	v_mov_b32_e32 v82, v5
	v_mul_f32_e32 v5, v13, v4
	v_mul_f32_e32 v5, v68, v5
	v_bfe_u32 v6, v5, 16, 1
	v_mul_f32_e32 v3, v3, v4
	v_add3_u32 v5, v5, v6, s33
	v_mul_f32_e32 v3, v70, v3
	s_nop 1
	v_mov_b32_dpp v83, v82 quad_perm:[1,0,3,2] row_mask:0xf bank_mask:0xf
	v_mov_b32_dpp v84, v5 quad_perm:[1,0,3,2] row_mask:0xf bank_mask:0xf
	v_perm_b32 v85, v83, v82, s98
	v_perm_b32 v86, v5, v84, s98
	v_cndmask_b32_e64 v85, v85, v86, s[100:101]
	v_lshl_add_u64 v[88:89], v[0:1], 0, v[90:91]
	global_store_dword v[88:89], v85, off
	v_bfe_u32 v5, v3, 16, 1
	v_mul_f32_e32 v2, v2, v4
	v_add3_u32 v3, v3, v5, s33
	v_mul_f32_e32 v2, v69, v2
	v_mov_b32_e32 v82, v3
	v_bfe_u32 v3, v2, 16, 1
	v_add3_u32 v2, v2, v3, s33
	s_nop 1
	v_mov_b32_dpp v83, v82 quad_perm:[1,0,3,2] row_mask:0xf bank_mask:0xf
	v_mov_b32_dpp v84, v2 quad_perm:[1,0,3,2] row_mask:0xf bank_mask:0xf
	v_perm_b32 v85, v83, v82, s98
	v_perm_b32 v86, v2, v84, s98
	v_cndmask_b32_e64 v85, v85, v86, s[100:101]
	v_lshl_add_u64 v[88:89], v[0:1], 0, v[90:91]
	global_store_dword v[88:89], v85, off offset:128
	v_lshlrev_b32_e32 v250, 4, v187
	v_add_u32_e32 v250, 0x18000, v250
	ds_read_b128 v[82:85], v250
	ds_read_b128 v[86:89], v250 offset:8192
	ds_read_b128 v[90:93], v250 offset:16384
	ds_read_b128 v[94:97], v250 offset:24576
	s_waitcnt lgkmcnt(0)
	s_cbranch_scc1 .LBB0_337

; #define LAS __attribute__((address_space(3)))
; DI unsigned f2bf(float f) { unsigned u = __builtin_bit_cast(unsigned, f); return (u + 0x7fffu + ((u >> 16) & 1u)) >> 16; }
; DI float shx(float v, int o, int lane) { return __int_as_float(__builtin_amdgcn_ds_bpermute((lane ^ o) << 2, __float_as_int(v))); }
; DI int crow(int i, int hh) { return (i & 3) + 8 * (i >> 2) + 4 * hh; }
; DI void attn_item(CArgs& a, LAS unsigned char* lds, int l, int b, int h, int qb, int tid_, int wave, int lane_) {
;     int tid = tid_; asm volatile("" : "+v"(tid)); const int lane = tid & 63;
;     LAS float* scr = (LAS float*)(lds + AT_SCR) + wave * 64;
;     const int r = lane & 31, hh = lane >> 5;
;     const int qloc = qb * 256 + wave * 32 + r; const size_t tq = (size_t)b * S_ + qloc;
;     ...
;     const float ltot = l_run + shx(l_run, 32, lane);
;     if (hh == 0) scr[r] = 1.f / ltot;
;     asm volatile("s_waitcnt lgkmcnt(0)" ::: "memory");
;     bf16_t* mix = (bf16_t*)(a.ws + WS_BUFA);
;     const size_t trow0 = (size_t)b * S_ + qb * 256 + wave * 32;
; #pragma unroll
;     for (int i = 0; i < 16; ++i) { const float inv = scr[crow(i, hh)]; float s = 0.f;
; #pragma unroll
;         for (int vt = 0; vt < 4; ++vt) { o[vt][i] *= inv; s += o[vt][i] * o[vt][i]; }
;         s += shx(s, 1, lane); s += shx(s, 2, lane); s += shx(s, 4, lane); s += shx(s, 8, lane); s += shx(s, 16, lane);
;         const float rs = rsqrtf(s * (1.f / 128.f) + EPS);
; #pragma unroll
;         for (int vt = 0; vt < 4; ++vt) { const int col = h * 128 + 32 * vt + r; mix[(trow0 + crow(i, hh)) * DM + 1024 + col] = (bf16_t)f2bf(o[vt][i] * rs * a.in[I_MIXG][l * DM + 1024 + col]); } }
.LBB0_316:
	s_or_b64 exec, exec, s[0:1]
	s_mov_b32 s98, 0x7060302
	s_mov_b32 s100, 0xaaaaaaaa
	s_mov_b32 s101, 0xaaaaaaaa
	v_mbcnt_lo_u32_b32 v90, -1, 0
	v_mbcnt_hi_u32_b32 v90, -1, v90
	v_and_b32_e32 v90, 1, v90
	v_mul_u32_u24_e32 v90, 62, v90
	v_mov_b32_e32 v91, 0
	s_waitcnt lgkmcnt(0)
	v_lshl_add_u32 v74, v195, 2, s27
	ds_read_b128 v[76:79], v74
	v_or_b32_e32 v70, s43, v169
	s_or_b32 s0, s14, s49
	v_or_b32_e32 v80, s92, v70
	s_add_u32 s0, s0, s26
	s_waitcnt lgkmcnt(1)
	v_mov_b32_e32 v64, v0
	v_mov_b32_e32 v65, v16
	v_lshl_add_u64 v[106:107], v[80:81], 2, s[8:9]
	s_movk_i32 s49, 0x1000
	s_addc_u32 s1, s15, s40
	s_waitcnt lgkmcnt(0)
	v_pk_mul_f32 v[98:99], v[64:65], v[76:77] op_sel_hi:[1,0]
	v_mov_b32_e32 v64, v48
	v_mov_b32_e32 v65, v32
	v_add_co_u32_e32 v106, vcc, s49, v106
	v_pk_mul_f32 v[102:103], v[64:65], v[76:77] op_sel_hi:[1,0]
	v_or_b32_e32 v64, s0, v195
	v_mov_b32_e32 v65, s1
	v_addc_co_u32_e32 v107, vcc, 0, v107, vcc
	v_lshlrev_b64 v[68:69], 12, v[64:65]
	global_load_dword v48, v[106:107], off
	v_lshl_add_u64 v[68:69], s[12:13], 0, v[68:69]
	v_lshlrev_b32_e32 v80, 1, v70
	v_lshl_add_u64 v[106:107], v[68:69], 0, v[80:81]
	v_add_u32_e32 v68, s92, v70
	v_mov_b32_e32 v69, v81
	v_lshl_add_u64 v[68:69], v[68:69], 2, s[8:9]
	v_add_co_u32_e32 v108, vcc, s49, v68
	v_mov_b32_e32 v16, v1
	s_nop 0
	v_addc_co_u32_e32 v109, vcc, 0, v69, vcc
	global_load_dword v68, v[108:109], off offset:128
	global_load_dword v70, v[108:109], off offset:256
	global_load_dword v69, v[108:109], off offset:384
	v_pk_mul_f32 v[0:1], v[16:17], v[76:77] op_sel:[0,1]
	v_mov_b32_e32 v32, v49
	v_pk_mul_f32 v[100:101], v[98:99], v[98:99]
	v_pk_mul_f32 v[16:17], v[0:1], v[0:1]
	v_pk_mul_f32 v[32:33], v[32:33], v[76:77] op_sel:[0,1]
	v_pk_mul_f32 v[104:105], v[102:103], v[102:103]
	v_pk_mul_f32 v[76:77], v[32:33], v[32:33]
	v_mov_b32_e32 v108, v16
	v_mov_b32_e32 v109, v100
	v_mov_b32_e32 v100, v17
	v_pk_add_f32 v[16:17], v[108:109], v[100:101]
	v_mov_b32_e32 v100, v77
	v_mov_b32_e32 v101, v105
	v_pk_add_f32 v[16:17], v[100:101], v[16:17]
	v_mov_b32_e32 v77, v104
	v_xor_b32_e32 v73, 4, v196
	v_pk_add_f32 v[16:17], v[76:77], v[16:17]
	ds_bpermute_b32 v77, v73, v17
	ds_bpermute_b32 v76, v73, v16
	v_xor_b32_e32 v72, 8, v196
	v_xor_b32_e32 v71, 16, v196
	v_xor_b32_e32 v67, 32, v196
	v_xor_b32_e32 v66, 64, v196
	s_waitcnt lgkmcnt(0)
	v_pk_add_f32 v[16:17], v[16:17], v[76:77]
	ds_bpermute_b32 v77, v72, v17
	ds_bpermute_b32 v76, v72, v16
	v_or_b32_e32 v100, 2, v64
	v_mov_b32_e32 v101, s1
	v_lshlrev_b64 v[100:101], 12, v[100:101]
	v_lshl_add_u64 v[100:101], s[12:13], 0, v[100:101]
	s_waitcnt lgkmcnt(0)
	v_pk_add_f32 v[16:17], v[16:17], v[76:77]
	ds_bpermute_b32 v77, v71, v17
	ds_bpermute_b32 v76, v71, v16
	v_lshl_add_u64 v[100:101], v[100:101], 0, v[80:81]
	s_xor_b32 s0, s47, 63
	s_lshl_b32 s5, s0, 8
	s_lshl_b32 s36, s48, 1
	s_waitcnt lgkmcnt(0)
	v_pk_add_f32 v[16:17], v[16:17], v[76:77]
	ds_bpermute_b32 v77, v67, v17
	ds_bpermute_b32 v76, v67, v16
	v_readlane_b32 s50, v253, 11
	s_mov_b32 s4, 0
	v_mov_b32_e32 v203, 0
	v_mov_b32_e32 v204, 0xff800000
	s_waitcnt lgkmcnt(0)
	v_pk_add_f32 v[16:17], v[16:17], v[76:77]
	ds_bpermute_b32 v77, v66, v17
	ds_bpermute_b32 v76, v66, v16
	v_readlane_b32 s54, v254, 2
	s_movk_i32 s55, 0x1a00
	v_readlane_b32 s51, v253, 12
	s_waitcnt lgkmcnt(0)
	v_pk_add_f32 v[76:77], v[16:17], v[76:77]
	v_mov_b64_e32 v[16:17], s[76:77]
	v_pk_fma_f32 v[76:77], v[76:77], s[78:79], v[16:17] op_sel_hi:[1,0,0]
	s_nop 0
	v_mul_f32_e32 v49, 0x4b800000, v77
	v_cmp_gt_f32_e64 s[6:7], s64, v77
	v_cmp_gt_f32_e32 vcc, s64, v76
	s_nop 0
	v_cndmask_b32_e64 v49, v77, v49, s[6:7]
	v_rsq_f32_e32 v49, v49
	s_nop 0
	v_mul_f32_e32 v75, 0x45800000, v49
	v_cndmask_b32_e64 v49, v49, v75, s[6:7]
	v_mul_f32_e32 v75, v98, v49
	s_waitcnt vmcnt(3)
	v_mul_f32_e32 v75, v48, v75
	v_bfe_u32 v77, v75, 16, 1
	v_add3_u32 v75, v75, v77, s33
	v_mov_b32_e32 v82, v75
	v_mul_f32_e32 v75, v99, v49
	s_waitcnt vmcnt(2)
	v_mul_f32_e32 v75, v68, v75
	v_bfe_u32 v77, v75, 16, 1
	v_add3_u32 v75, v75, v77, s33
	s_nop 1
	v_mov_b32_dpp v83, v82 quad_perm:[1,0,3,2] row_mask:0xf bank_mask:0xf
	v_mov_b32_dpp v84, v75 quad_perm:[1,0,3,2] row_mask:0xf bank_mask:0xf
	v_perm_b32 v85, v83, v82, s98
	v_perm_b32 v86, v75, v84, s98
	v_cndmask_b32_e64 v85, v85, v86, s[100:101]
	v_lshl_add_u64 v[88:89], v[106:107], 0, v[90:91]
	global_store_dword v[88:89], v85, off
	v_mul_f32_e32 v75, v103, v49
	s_waitcnt vmcnt(2)
	v_mul_f32_e32 v75, v70, v75
	v_bfe_u32 v77, v75, 16, 1
	v_mul_f32_e32 v49, v102, v49
	v_add3_u32 v75, v75, v77, s33
	s_waitcnt vmcnt(1)
; DI unsigned f2bf(float f) { unsigned u = __builtin_bit_cast(unsigned, f); return (u + 0x7fffu + ((u >> 16) & 1u)) >> 16; }
; DI float shx(float v, int o, int lane) { return __int_as_float(__builtin_amdgcn_ds_bpermute((lane ^ o) << 2, __float_as_int(v))); }
; DI int crow(int i, int hh) { return (i & 3) + 8 * (i >> 2) + 4 * hh; }
; DI void attn_item(CArgs& a, LAS unsigned char* lds, int l, int b, int h, int qb, int tid_, int wave, int lane_) {
;     ...
;     for (int i = 0; i < 16; ++i) { const float inv = scr[crow(i, hh)]; float s = 0.f;
; #pragma unroll
;         for (int vt = 0; vt < 4; ++vt) { o[vt][i] *= inv; s += o[vt][i] * o[vt][i]; }
;         s += shx(s, 1, lane); s += shx(s, 2, lane); s += shx(s, 4, lane); s += shx(s, 8, lane); s += shx(s, 16, lane);
;         const float rs = rsqrtf(s * (1.f / 128.f) + EPS);
; #pragma unroll
;         for (int vt = 0; vt < 4; ++vt) { const int col = h * 128 + 32 * vt + r; mix[(trow0 + crow(i, hh)) * DM + 1024 + col] = (bf16_t)f2bf(o[vt][i] * rs * a.in[I_MIXG][l * DM + 1024 + col]); } }
	v_mul_f32_e32 v49, v69, v49
	v_mov_b32_e32 v82, v75
	v_bfe_u32 v75, v49, 16, 1
	v_add3_u32 v49, v49, v75, s33
	s_nop 1
	v_mov_b32_dpp v83, v82 quad_perm:[1,0,3,2] row_mask:0xf bank_mask:0xf
	v_mov_b32_dpp v84, v49 quad_perm:[1,0,3,2] row_mask:0xf bank_mask:0xf
	v_perm_b32 v85, v83, v82, s98
	v_perm_b32 v86, v49, v84, s98
	v_cndmask_b32_e64 v85, v85, v86, s[100:101]
	v_lshl_add_u64 v[88:89], v[106:107], 0, v[90:91]
	global_store_dword v[88:89], v85, off offset:128
	v_mul_f32_e32 v49, 0x4b800000, v76
	v_cndmask_b32_e32 v49, v76, v49, vcc
	v_rsq_f32_e32 v49, v49
	v_or_b32_e32 v76, 1, v64
	v_mov_b32_e32 v77, s1
	v_lshlrev_b64 v[76:77], 12, v[76:77]
	v_mul_f32_e32 v75, 0x45800000, v49
	v_cndmask_b32_e32 v49, v49, v75, vcc
	v_mul_f32_e32 v0, v0, v49
	v_mul_f32_e32 v0, v48, v0
	v_lshl_add_u64 v[76:77], s[12:13], 0, v[76:77]
	v_bfe_u32 v75, v0, 16, 1
	v_add3_u32 v0, v0, v75, s33
	v_lshl_add_u64 v[76:77], v[76:77], 0, v[80:81]
	v_mov_b32_e32 v82, v0
	v_mul_f32_e32 v0, v1, v49
	v_mul_f32_e32 v0, v68, v0
	v_bfe_u32 v1, v0, 16, 1
	v_add3_u32 v0, v0, v1, s33
	s_nop 1
	v_mov_b32_dpp v83, v82 quad_perm:[1,0,3,2] row_mask:0xf bank_mask:0xf
	v_mov_b32_dpp v84, v0 quad_perm:[1,0,3,2] row_mask:0xf bank_mask:0xf
	v_perm_b32 v85, v83, v82, s98
	v_perm_b32 v86, v0, v84, s98
	v_cndmask_b32_e64 v85, v85, v86, s[100:101]
	v_lshl_add_u64 v[88:89], v[76:77], 0, v[90:91]
	global_store_dword v[88:89], v85, off
	v_mul_f32_e32 v0, v33, v49
	v_mul_f32_e32 v0, v70, v0
	v_bfe_u32 v1, v0, 16, 1
	v_add3_u32 v0, v0, v1, s33
	v_mov_b32_e32 v82, v0
	v_mul_f32_e32 v0, v32, v49
	v_mul_f32_e32 v0, v69, v0
	v_bfe_u32 v1, v0, 16, 1
	v_add3_u32 v0, v0, v1, s33
	s_nop 1
	v_mov_b32_dpp v83, v82 quad_perm:[1,0,3,2] row_mask:0xf bank_mask:0xf
	v_mov_b32_dpp v84, v0 quad_perm:[1,0,3,2] row_mask:0xf bank_mask:0xf
	v_perm_b32 v85, v83, v82, s98
	v_perm_b32 v86, v0, v84, s98
	v_cndmask_b32_e64 v85, v85, v86, s[100:101]
	v_lshl_add_u64 v[88:89], v[76:77], 0, v[90:91]
	global_store_dword v[88:89], v85, off offset:128
	v_mov_b32_e32 v0, v2
	v_mov_b32_e32 v1, v18
	v_mov_b32_e32 v18, v3
	v_mov_b32_e32 v2, v79
	v_pk_mul_f32 v[0:1], v[0:1], v[78:79] op_sel_hi:[1,0]
	v_mov_b32_e32 v76, v50
	v_mov_b32_e32 v77, v34
	v_pk_mul_f32 v[18:19], v[18:19], v[2:3] op_sel_hi:[1,0]
	v_mov_b32_e32 v34, v51
	v_pk_mul_f32 v[32:33], v[0:1], v[0:1]
	v_pk_mul_f32 v[76:77], v[76:77], v[78:79] op_sel_hi:[1,0]
	v_pk_mul_f32 v[78:79], v[18:19], v[18:19]
	v_pk_mul_f32 v[2:3], v[34:35], v[2:3] op_sel_hi:[1,0]
	v_pk_mul_f32 v[98:99], v[76:77], v[76:77]
	v_pk_mul_f32 v[34:35], v[2:3], v[2:3]
	v_mov_b32_e32 v50, v78
	v_mov_b32_e32 v51, v32
	v_mov_b32_e32 v32, v79
	v_pk_add_f32 v[32:33], v[50:51], v[32:33]
	v_mov_b32_e32 v50, v35
	v_mov_b32_e32 v51, v99
	v_pk_add_f32 v[32:33], v[50:51], v[32:33]
	v_mov_b32_e32 v35, v98
	v_pk_add_f32 v[32:33], v[34:35], v[32:33]
	ds_bpermute_b32 v35, v73, v33
	ds_bpermute_b32 v34, v73, v32
	v_mov_b32_e32 v49, v81
	s_waitcnt lgkmcnt(0)
	v_pk_add_f32 v[32:33], v[32:33], v[34:35]
	ds_bpermute_b32 v35, v72, v33
	ds_bpermute_b32 v34, v72, v32
	s_waitcnt lgkmcnt(0)
	v_pk_add_f32 v[32:33], v[32:33], v[34:35]
	ds_bpermute_b32 v35, v71, v33
	ds_bpermute_b32 v34, v71, v32
	s_waitcnt lgkmcnt(0)
	v_pk_add_f32 v[32:33], v[32:33], v[34:35]
	ds_bpermute_b32 v35, v67, v33
	ds_bpermute_b32 v34, v67, v32
	s_waitcnt lgkmcnt(0)
	v_pk_add_f32 v[32:33], v[32:33], v[34:35]
	ds_bpermute_b32 v35, v66, v33
	ds_bpermute_b32 v34, v66, v32
	s_waitcnt lgkmcnt(0)
	v_pk_add_f32 v[32:33], v[32:33], v[34:35]
	s_nop 0
	v_pk_fma_f32 v[32:33], v[32:33], s[78:79], v[16:17] op_sel_hi:[1,0,0]
	v_mov_b32_e32 v35, v36
	v_mul_f32_e32 v34, 0x4b800000, v33
	v_cmp_gt_f32_e64 s[6:7], s64, v33
	v_cmp_gt_f32_e32 vcc, s64, v32
	v_mov_b32_e32 v36, v53
	v_cndmask_b32_e64 v33, v33, v34, s[6:7]
	v_rsq_f32_e32 v33, v33
	s_nop 0
	v_mul_f32_e32 v34, 0x45800000, v33
	v_cndmask_b32_e64 v33, v33, v34, s[6:7]
	v_mul_f32_e32 v0, v0, v33
	v_mul_f32_e32 v0, v48, v0
	v_bfe_u32 v34, v0, 16, 1
	v_add3_u32 v0, v0, v34, s33
	v_mov_b32_e32 v82, v0
	v_mul_f32_e32 v0, v1, v33
	v_mul_f32_e32 v0, v68, v0
	v_bfe_u32 v1, v0, 16, 1
	v_add3_u32 v0, v0, v1, s33
	s_nop 1
	v_mov_b32_dpp v83, v82 quad_perm:[1,0,3,2] row_mask:0xf bank_mask:0xf
	v_mov_b32_dpp v84, v0 quad_perm:[1,0,3,2] row_mask:0xf bank_mask:0xf
	v_perm_b32 v85, v83, v82, s98
	v_perm_b32 v86, v0, v84, s98
	v_cndmask_b32_e64 v85, v85, v86, s[100:101]
	v_lshl_add_u64 v[88:89], v[100:101], 0, v[90:91]
	global_store_dword v[88:89], v85, off
	v_mul_f32_e32 v0, v77, v33
	v_mul_f32_e32 v0, v70, v0
	v_bfe_u32 v1, v0, 16, 1
	v_add3_u32 v0, v0, v1, s33
	v_mov_b32_e32 v82, v0
	v_mul_f32_e32 v0, v76, v33
	v_mul_f32_e32 v0, v69, v0
	v_bfe_u32 v1, v0, 16, 1
	v_add3_u32 v0, v0, v1, s33
	s_nop 1
	v_mov_b32_dpp v83, v82 quad_perm:[1,0,3,2] row_mask:0xf bank_mask:0xf
	v_mov_b32_dpp v84, v0 quad_perm:[1,0,3,2] row_mask:0xf bank_mask:0xf
	v_perm_b32 v85, v83, v82, s98
	v_perm_b32 v86, v0, v84, s98
	v_cndmask_b32_e64 v85, v85, v86, s[100:101]
	v_lshl_add_u64 v[88:89], v[100:101], 0, v[90:91]
	global_store_dword v[88:89], v85, off offset:128
	v_mul_f32_e32 v0, 0x4b800000, v32
	v_cndmask_b32_e32 v0, v32, v0, vcc
	v_rsq_f32_e32 v0, v0
	v_mov_b32_e32 v34, v52
	v_or_b32_e32 v76, 8, v64
	v_mov_b32_e32 v77, s1
	v_mul_f32_e32 v1, 0x45800000, v0
	v_cndmask_b32_e32 v32, v0, v1, vcc
	v_or_b32_e32 v0, 3, v64
	v_mov_b32_e32 v1, s1
	v_mul_f32_e32 v18, v18, v32
	v_lshlrev_b64 v[0:1], 12, v[0:1]
	v_mul_f32_e32 v18, v48, v18
	v_lshl_add_u64 v[0:1], s[12:13], 0, v[0:1]
	v_bfe_u32 v33, v18, 16, 1
	v_add3_u32 v18, v18, v33, s33
	v_lshl_add_u64 v[0:1], v[0:1], 0, v[80:81]
	v_mov_b32_e32 v82, v18
	v_mul_f32_e32 v18, v19, v32
	v_mul_f32_e32 v18, v68, v18
	v_bfe_u32 v19, v18, 16, 1
	v_mul_f32_e32 v3, v3, v32
	v_add3_u32 v18, v18, v19, s33
	v_mul_f32_e32 v3, v70, v3
	s_nop 1
	v_mov_b32_dpp v83, v82 quad_perm:[1,0,3,2] row_mask:0xf bank_mask:0xf
	v_mov_b32_dpp v84, v18 quad_perm:[1,0,3,2] row_mask:0xf bank_mask:0xf
	v_perm_b32 v85, v83, v82, s98
	v_perm_b32 v86, v18, v84, s98
	v_cndmask_b32_e64 v85, v85, v86, s[100:101]
	v_lshl_add_u64 v[88:89], v[0:1], 0, v[90:91]
	global_store_dword v[88:89], v85, off
	v_bfe_u32 v18, v3, 16, 1
	v_mul_f32_e32 v2, v2, v32
	v_add3_u32 v3, v3, v18, s33
	v_mul_f32_e32 v2, v69, v2
	v_mov_b32_e32 v82, v3
	v_bfe_u32 v3, v2, 16, 1
	v_add3_u32 v2, v2, v3, s33
	s_nop 1
	v_mov_b32_dpp v83, v82 quad_perm:[1,0,3,2] row_mask:0xf bank_mask:0xf
	v_mov_b32_dpp v84, v2 quad_perm:[1,0,3,2] row_mask:0xf bank_mask:0xf
	v_perm_b32 v85, v83, v82, s98
	v_perm_b32 v86, v2, v84, s98
	v_cndmask_b32_e64 v85, v85, v86, s[100:101]
	v_lshl_add_u64 v[88:89], v[0:1], 0, v[90:91]
	global_store_dword v[88:89], v85, off offset:128
	ds_read_b128 v[0:3], v74 offset:32
	v_mov_b32_e32 v18, v4
	v_mov_b32_e32 v19, v20
	v_mov_b32_e32 v20, v5
	v_lshlrev_b64 v[76:77], 12, v[76:77]
	s_waitcnt lgkmcnt(0)
; DI unsigned f2bf(float f) { unsigned u = __builtin_bit_cast(unsigned, f); return (u + 0x7fffu + ((u >> 16) & 1u)) >> 16; }
; DI float shx(float v, int o, int lane) { return __int_as_float(__builtin_amdgcn_ds_bpermute((lane ^ o) << 2, __float_as_int(v))); }
; DI int crow(int i, int hh) { return (i & 3) + 8 * (i >> 2) + 4 * hh; }
; DI void attn_item(CArgs& a, LAS unsigned char* lds, int l, int b, int h, int qb, int tid_, int wave, int lane_) {
;     ...
;     for (int i = 0; i < 16; ++i) { const float inv = scr[crow(i, hh)]; float s = 0.f;
; #pragma unroll
;         for (int vt = 0; vt < 4; ++vt) { o[vt][i] *= inv; s += o[vt][i] * o[vt][i]; }
;         s += shx(s, 1, lane); s += shx(s, 2, lane); s += shx(s, 4, lane); s += shx(s, 8, lane); s += shx(s, 16, lane);
;         const float rs = rsqrtf(s * (1.f / 128.f) + EPS);
; #pragma unroll
;         for (int vt = 0; vt < 4; ++vt) { const int col = h * 128 + 32 * vt + r; mix[(trow0 + crow(i, hh)) * DM + 1024 + col] = (bf16_t)f2bf(o[vt][i] * rs * a.in[I_MIXG][l * DM + 1024 + col]); } }
	v_pk_mul_f32 v[18:19], v[18:19], v[0:1] op_sel_hi:[1,0]
	v_pk_mul_f32 v[4:5], v[20:21], v[0:1] op_sel:[0,1]
	v_pk_mul_f32 v[32:33], v[18:19], v[18:19]
	v_pk_mul_f32 v[34:35], v[34:35], v[0:1] op_sel_hi:[1,0]
	v_pk_mul_f32 v[20:21], v[4:5], v[4:5]
	v_pk_mul_f32 v[0:1], v[36:37], v[0:1] op_sel:[0,1]
	v_pk_mul_f32 v[50:51], v[34:35], v[34:35]
	v_pk_mul_f32 v[36:37], v[0:1], v[0:1]
	v_mov_b32_e32 v52, v20
	v_mov_b32_e32 v53, v32
	v_mov_b32_e32 v32, v21
	v_pk_add_f32 v[20:21], v[52:53], v[32:33]
	v_mov_b32_e32 v32, v37
	v_mov_b32_e32 v33, v51
	v_pk_add_f32 v[20:21], v[32:33], v[20:21]
	v_mov_b32_e32 v37, v50
	v_pk_add_f32 v[20:21], v[36:37], v[20:21]
	ds_bpermute_b32 v33, v73, v21
	ds_bpermute_b32 v32, v73, v20
	v_lshl_add_u64 v[76:77], s[12:13], 0, v[76:77]
	v_lshl_add_u64 v[76:77], v[76:77], 0, v[80:81]
	v_mov_b32_e32 v50, v81
	v_mov_b32_e32 v51, v81
	s_waitcnt lgkmcnt(0)
	v_pk_add_f32 v[20:21], v[20:21], v[32:33]
	ds_bpermute_b32 v33, v72, v21
	ds_bpermute_b32 v32, v72, v20
	v_mov_b32_e32 v52, v81
	v_mov_b32_e32 v53, v81
	s_waitcnt lgkmcnt(0)
	v_pk_add_f32 v[20:21], v[20:21], v[32:33]
	ds_bpermute_b32 v33, v71, v21
	ds_bpermute_b32 v32, v71, v20
	s_waitcnt lgkmcnt(0)
	v_pk_add_f32 v[20:21], v[20:21], v[32:33]
	ds_bpermute_b32 v33, v67, v21
	ds_bpermute_b32 v32, v67, v20
	s_waitcnt lgkmcnt(0)
	v_pk_add_f32 v[20:21], v[20:21], v[32:33]
	ds_bpermute_b32 v33, v66, v21
	ds_bpermute_b32 v32, v66, v20
	s_waitcnt lgkmcnt(0)
	v_pk_add_f32 v[20:21], v[20:21], v[32:33]
	s_nop 0
	v_pk_fma_f32 v[20:21], v[20:21], s[78:79], v[16:17] op_sel_hi:[1,0,0]
	v_mov_b32_e32 v33, s1
	v_mul_f32_e32 v32, 0x4b800000, v21
	v_cmp_gt_f32_e64 s[6:7], s64, v21
	v_cmp_gt_f32_e32 vcc, s64, v20
	s_nop 0
	v_cndmask_b32_e64 v21, v21, v32, s[6:7]
	v_rsq_f32_e32 v21, v21
	s_nop 0
	v_mul_f32_e32 v32, 0x45800000, v21
	v_cndmask_b32_e64 v21, v21, v32, s[6:7]
	v_mul_f32_e32 v18, v18, v21
	v_mul_f32_e32 v18, v48, v18
	v_bfe_u32 v32, v18, 16, 1
	v_add3_u32 v18, v18, v32, s33
	v_mov_b32_e32 v82, v18
	v_mul_f32_e32 v18, v19, v21
	v_mul_f32_e32 v18, v68, v18
	v_bfe_u32 v19, v18, 16, 1
	v_add3_u32 v18, v18, v19, s33
	s_nop 1
	v_mov_b32_dpp v83, v82 quad_perm:[1,0,3,2] row_mask:0xf bank_mask:0xf
	v_mov_b32_dpp v84, v18 quad_perm:[1,0,3,2] row_mask:0xf bank_mask:0xf
	v_perm_b32 v85, v83, v82, s98
	v_perm_b32 v86, v18, v84, s98
	v_cndmask_b32_e64 v85, v85, v86, s[100:101]
	v_lshl_add_u64 v[88:89], v[76:77], 0, v[90:91]
	global_store_dword v[88:89], v85, off
	v_mul_f32_e32 v18, v35, v21
	v_mul_f32_e32 v18, v70, v18
	v_bfe_u32 v19, v18, 16, 1
	v_add3_u32 v18, v18, v19, s33
	v_mov_b32_e32 v82, v18
	v_mul_f32_e32 v18, v34, v21
	v_mul_f32_e32 v18, v69, v18
	v_bfe_u32 v19, v18, 16, 1
	v_add3_u32 v18, v18, v19, s33
	s_nop 1
	v_mov_b32_dpp v83, v82 quad_perm:[1,0,3,2] row_mask:0xf bank_mask:0xf
	v_mov_b32_dpp v84, v18 quad_perm:[1,0,3,2] row_mask:0xf bank_mask:0xf
	v_perm_b32 v85, v83, v82, s98
	v_perm_b32 v86, v18, v84, s98
	v_cndmask_b32_e64 v85, v85, v86, s[100:101]
	v_lshl_add_u64 v[88:89], v[76:77], 0, v[90:91]
	global_store_dword v[88:89], v85, off offset:128
	v_mul_f32_e32 v18, 0x4b800000, v20
	v_cndmask_b32_e32 v18, v20, v18, vcc
	v_rsq_f32_e32 v18, v18
	v_or_b32_e32 v32, 10, v64
	v_lshlrev_b64 v[32:33], 12, v[32:33]
	v_lshl_add_u64 v[32:33], s[12:13], 0, v[32:33]
	v_mul_f32_e32 v19, 0x45800000, v18
	v_cndmask_b32_e32 v20, v18, v19, vcc
	v_or_b32_e32 v18, 9, v64
	v_mov_b32_e32 v19, s1
	v_mul_f32_e32 v4, v4, v20
	v_lshlrev_b64 v[18:19], 12, v[18:19]
	v_mul_f32_e32 v4, v48, v4
	v_lshl_add_u64 v[18:19], s[12:13], 0, v[18:19]
	v_bfe_u32 v21, v4, 16, 1
	v_add3_u32 v4, v4, v21, s33
	v_lshl_add_u64 v[18:19], v[18:19], 0, v[80:81]
	v_mov_b32_e32 v82, v4
	v_mul_f32_e32 v4, v5, v20
	v_mul_f32_e32 v4, v68, v4
	v_bfe_u32 v5, v4, 16, 1
	v_mul_f32_e32 v1, v1, v20
	v_add3_u32 v4, v4, v5, s33
	v_mul_f32_e32 v1, v70, v1
	s_nop 1
	v_mov_b32_dpp v83, v82 quad_perm:[1,0,3,2] row_mask:0xf bank_mask:0xf
	v_mov_b32_dpp v84, v4 quad_perm:[1,0,3,2] row_mask:0xf bank_mask:0xf
	v_perm_b32 v85, v83, v82, s98
	v_perm_b32 v86, v4, v84, s98
	v_cndmask_b32_e64 v85, v85, v86, s[100:101]
	v_lshl_add_u64 v[88:89], v[18:19], 0, v[90:91]
	global_store_dword v[88:89], v85, off
	v_bfe_u32 v4, v1, 16, 1
	v_mul_f32_e32 v0, v0, v20
	v_add3_u32 v1, v1, v4, s33
	v_mul_f32_e32 v0, v69, v0
	v_mov_b32_e32 v82, v1
	v_bfe_u32 v1, v0, 16, 1
	v_add3_u32 v0, v0, v1, s33
	s_nop 1
	v_mov_b32_dpp v83, v82 quad_perm:[1,0,3,2] row_mask:0xf bank_mask:0xf
	v_mov_b32_dpp v84, v0 quad_perm:[1,0,3,2] row_mask:0xf bank_mask:0xf
	v_perm_b32 v85, v83, v82, s98
	v_perm_b32 v86, v0, v84, s98
	v_cndmask_b32_e64 v85, v85, v86, s[100:101]
	v_lshl_add_u64 v[88:89], v[18:19], 0, v[90:91]
	global_store_dword v[88:89], v85, off offset:128
	v_mov_b32_e32 v0, v6
	v_mov_b32_e32 v1, v22
	v_mov_b32_e32 v18, v54
	v_mov_b32_e32 v19, v38
	v_pk_mul_f32 v[0:1], v[0:1], v[2:3] op_sel_hi:[1,0]
	v_pk_mul_f32 v[18:19], v[18:19], v[2:3] op_sel_hi:[1,0]
	v_mov_b32_e32 v22, v7
	v_mov_b32_e32 v2, v3
	v_pk_mul_f32 v[6:7], v[22:23], v[2:3] op_sel_hi:[1,0]
	v_mov_b32_e32 v38, v55
	v_pk_mul_f32 v[4:5], v[0:1], v[0:1]
	v_pk_mul_f32 v[22:23], v[6:7], v[6:7]
	v_pk_mul_f32 v[2:3], v[38:39], v[2:3] op_sel_hi:[1,0]
	v_pk_mul_f32 v[20:21], v[18:19], v[18:19]
	v_pk_mul_f32 v[34:35], v[2:3], v[2:3]
	v_mov_b32_e32 v36, v22
	v_mov_b32_e32 v37, v4
	v_mov_b32_e32 v4, v23
	v_pk_add_f32 v[4:5], v[36:37], v[4:5]
	v_mov_b32_e32 v22, v35
	v_mov_b32_e32 v23, v21
	v_pk_add_f32 v[4:5], v[22:23], v[4:5]
	v_mov_b32_e32 v35, v20
	v_pk_add_f32 v[4:5], v[34:35], v[4:5]
	ds_bpermute_b32 v21, v73, v5
	ds_bpermute_b32 v20, v73, v4
	v_lshl_add_u64 v[32:33], v[32:33], 0, v[80:81]
	v_or_b32_e32 v22, 16, v64
	v_mov_b32_e32 v23, s1
	v_lshlrev_b64 v[22:23], 12, v[22:23]
	s_waitcnt lgkmcnt(0)
; DI unsigned f2bf(float f) { unsigned u = __builtin_bit_cast(unsigned, f); return (u + 0x7fffu + ((u >> 16) & 1u)) >> 16; }
; DI float shx(float v, int o, int lane) { return __int_as_float(__builtin_amdgcn_ds_bpermute((lane ^ o) << 2, __float_as_int(v))); }
; DI int crow(int i, int hh) { return (i & 3) + 8 * (i >> 2) + 4 * hh; }
; DI void attn_item(CArgs& a, LAS unsigned char* lds, int l, int b, int h, int qb, int tid_, int wave, int lane_) {
;     ...
;     for (int i = 0; i < 16; ++i) { const float inv = scr[crow(i, hh)]; float s = 0.f;
; #pragma unroll
;         for (int vt = 0; vt < 4; ++vt) { o[vt][i] *= inv; s += o[vt][i] * o[vt][i]; }
;         s += shx(s, 1, lane); s += shx(s, 2, lane); s += shx(s, 4, lane); s += shx(s, 8, lane); s += shx(s, 16, lane);
;         const float rs = rsqrtf(s * (1.f / 128.f) + EPS);
; #pragma unroll
;         for (int vt = 0; vt < 4; ++vt) { const int col = h * 128 + 32 * vt + r; mix[(trow0 + crow(i, hh)) * DM + 1024 + col] = (bf16_t)f2bf(o[vt][i] * rs * a.in[I_MIXG][l * DM + 1024 + col]); } }
	v_pk_add_f32 v[4:5], v[4:5], v[20:21]
	ds_bpermute_b32 v21, v72, v5
	ds_bpermute_b32 v20, v72, v4
	v_lshl_add_u64 v[22:23], s[12:13], 0, v[22:23]
	v_lshl_add_u64 v[22:23], v[22:23], 0, v[80:81]
	v_mov_b32_e32 v77, v187
	v_mov_b32_e32 v36, v81
	s_waitcnt lgkmcnt(0)
	v_pk_add_f32 v[4:5], v[4:5], v[20:21]
	ds_bpermute_b32 v21, v71, v5
	ds_bpermute_b32 v20, v71, v4
	v_mov_b32_e32 v37, v81
	v_mov_b32_e32 v38, v81
	v_mov_b32_e32 v39, v81
	v_mov_b32_e32 v54, v81
	s_waitcnt lgkmcnt(0)
	v_pk_add_f32 v[4:5], v[4:5], v[20:21]
	ds_bpermute_b32 v21, v67, v5
	ds_bpermute_b32 v20, v67, v4
	v_mov_b32_e32 v55, v81
	s_waitcnt lgkmcnt(0)
	v_pk_add_f32 v[4:5], v[4:5], v[20:21]
	ds_bpermute_b32 v21, v66, v5
	ds_bpermute_b32 v20, v66, v4
	s_waitcnt lgkmcnt(0)
	v_pk_add_f32 v[4:5], v[4:5], v[20:21]
	s_nop 0
	v_pk_fma_f32 v[4:5], v[4:5], s[78:79], v[16:17] op_sel_hi:[1,0,0]
	s_nop 0
	v_mul_f32_e32 v20, 0x4b800000, v5
	v_cmp_gt_f32_e64 s[6:7], s64, v5
	v_cmp_gt_f32_e32 vcc, s64, v4
	s_nop 0
	v_cndmask_b32_e64 v5, v5, v20, s[6:7]
	v_rsq_f32_e32 v5, v5
	s_nop 0
	v_mul_f32_e32 v20, 0x45800000, v5
	v_cndmask_b32_e64 v5, v5, v20, s[6:7]
	v_mul_f32_e32 v0, v0, v5
	v_mul_f32_e32 v0, v48, v0
	v_bfe_u32 v20, v0, 16, 1
	v_add3_u32 v0, v0, v20, s33
	v_mov_b32_e32 v82, v0
	v_mul_f32_e32 v0, v1, v5
	v_mul_f32_e32 v0, v68, v0
	v_bfe_u32 v1, v0, 16, 1
	v_add3_u32 v0, v0, v1, s33
	s_nop 1
	v_mov_b32_dpp v83, v82 quad_perm:[1,0,3,2] row_mask:0xf bank_mask:0xf
	v_mov_b32_dpp v84, v0 quad_perm:[1,0,3,2] row_mask:0xf bank_mask:0xf
	v_perm_b32 v85, v83, v82, s98
	v_perm_b32 v86, v0, v84, s98
	v_cndmask_b32_e64 v85, v85, v86, s[100:101]
	v_lshl_add_u64 v[88:89], v[32:33], 0, v[90:91]
	global_store_dword v[88:89], v85, off
	v_mul_f32_e32 v0, v19, v5
	v_mul_f32_e32 v0, v70, v0
	v_bfe_u32 v1, v0, 16, 1
	v_add3_u32 v0, v0, v1, s33
	v_mov_b32_e32 v82, v0
	v_mul_f32_e32 v0, v18, v5
	v_mul_f32_e32 v0, v69, v0
	v_bfe_u32 v1, v0, 16, 1
	v_add3_u32 v0, v0, v1, s33
	s_nop 1
	v_mov_b32_dpp v83, v82 quad_perm:[1,0,3,2] row_mask:0xf bank_mask:0xf
	v_mov_b32_dpp v84, v0 quad_perm:[1,0,3,2] row_mask:0xf bank_mask:0xf
	v_perm_b32 v85, v83, v82, s98
	v_perm_b32 v86, v0, v84, s98
	v_cndmask_b32_e64 v85, v85, v86, s[100:101]
	v_lshl_add_u64 v[88:89], v[32:33], 0, v[90:91]
	global_store_dword v[88:89], v85, off offset:128
	v_mul_f32_e32 v0, 0x4b800000, v4
	v_cndmask_b32_e32 v0, v4, v0, vcc
	v_rsq_f32_e32 v0, v0
	v_mov_b32_e32 v18, v56
	v_mov_b32_e32 v19, v40
	v_mov_b32_e32 v40, v57
	v_mul_f32_e32 v1, 0x45800000, v0
	v_cndmask_b32_e32 v4, v0, v1, vcc
	v_or_b32_e32 v0, 11, v64
	v_mov_b32_e32 v1, s1
	v_mul_f32_e32 v5, v6, v4
	v_lshlrev_b64 v[0:1], 12, v[0:1]
	v_mul_f32_e32 v5, v48, v5
	v_lshl_add_u64 v[0:1], s[12:13], 0, v[0:1]
	v_bfe_u32 v6, v5, 16, 1
	v_add3_u32 v5, v5, v6, s33
	v_lshl_add_u64 v[0:1], v[0:1], 0, v[80:81]
	v_mov_b32_e32 v82, v5
	v_mul_f32_e32 v5, v7, v4
	v_mul_f32_e32 v5, v68, v5
	v_bfe_u32 v6, v5, 16, 1
	v_mul_f32_e32 v3, v3, v4
	v_add3_u32 v5, v5, v6, s33
	v_mul_f32_e32 v3, v70, v3
	s_nop 1
	v_mov_b32_dpp v83, v82 quad_perm:[1,0,3,2] row_mask:0xf bank_mask:0xf
	v_mov_b32_dpp v84, v5 quad_perm:[1,0,3,2] row_mask:0xf bank_mask:0xf
	v_perm_b32 v85, v83, v82, s98
	v_perm_b32 v86, v5, v84, s98
	v_cndmask_b32_e64 v85, v85, v86, s[100:101]
	v_lshl_add_u64 v[88:89], v[0:1], 0, v[90:91]
	global_store_dword v[88:89], v85, off
	v_bfe_u32 v5, v3, 16, 1
	v_mul_f32_e32 v2, v2, v4
	v_add3_u32 v3, v3, v5, s33
	v_mul_f32_e32 v2, v69, v2
	v_mov_b32_e32 v82, v3
	v_bfe_u32 v3, v2, 16, 1
	v_add3_u32 v2, v2, v3, s33
	s_nop 1
	v_mov_b32_dpp v83, v82 quad_perm:[1,0,3,2] row_mask:0xf bank_mask:0xf
	v_mov_b32_dpp v84, v2 quad_perm:[1,0,3,2] row_mask:0xf bank_mask:0xf
	v_perm_b32 v85, v83, v82, s98
	v_perm_b32 v86, v2, v84, s98
	v_cndmask_b32_e64 v85, v85, v86, s[100:101]
	v_lshl_add_u64 v[88:89], v[0:1], 0, v[90:91]
	global_store_dword v[88:89], v85, off offset:128
	ds_read_b128 v[0:3], v74 offset:64
	v_mov_b32_e32 v4, v8
	v_mov_b32_e32 v5, v24
	v_mov_b32_e32 v24, v9
	v_mov_b32_e32 v56, v81
	s_waitcnt lgkmcnt(0)
	v_pk_mul_f32 v[4:5], v[4:5], v[0:1] op_sel_hi:[1,0]
	v_pk_mul_f32 v[8:9], v[24:25], v[0:1] op_sel:[0,1]
	v_pk_mul_f32 v[6:7], v[4:5], v[4:5]
	v_pk_mul_f32 v[18:19], v[18:19], v[0:1] op_sel_hi:[1,0]
	v_pk_mul_f32 v[24:25], v[8:9], v[8:9]
	v_pk_mul_f32 v[0:1], v[40:41], v[0:1] op_sel:[0,1]
	v_pk_mul_f32 v[20:21], v[18:19], v[18:19]
	v_pk_mul_f32 v[32:33], v[0:1], v[0:1]
	v_mov_b32_e32 v34, v24
	v_mov_b32_e32 v35, v6
	v_mov_b32_e32 v6, v25
	v_pk_add_f32 v[6:7], v[34:35], v[6:7]
	v_mov_b32_e32 v24, v33
	v_mov_b32_e32 v25, v21
	v_pk_add_f32 v[6:7], v[24:25], v[6:7]
	v_mov_b32_e32 v33, v20
	v_pk_add_f32 v[6:7], v[32:33], v[6:7]
	ds_bpermute_b32 v21, v73, v7
	ds_bpermute_b32 v20, v73, v6
	v_mov_b32_e32 v40, v81
	v_mov_b32_e32 v41, v81
	v_mov_b32_e32 v57, v81
	s_waitcnt lgkmcnt(0)
	v_pk_add_f32 v[6:7], v[6:7], v[20:21]
	ds_bpermute_b32 v21, v72, v7
	ds_bpermute_b32 v20, v72, v6
	s_waitcnt lgkmcnt(0)
	v_pk_add_f32 v[6:7], v[6:7], v[20:21]
	ds_bpermute_b32 v21, v71, v7
	ds_bpermute_b32 v20, v71, v6
	s_waitcnt lgkmcnt(0)
	v_pk_add_f32 v[6:7], v[6:7], v[20:21]
	ds_bpermute_b32 v21, v67, v7
	ds_bpermute_b32 v20, v67, v6
	s_waitcnt lgkmcnt(0)
	v_pk_add_f32 v[6:7], v[6:7], v[20:21]
	ds_bpermute_b32 v21, v66, v7
	ds_bpermute_b32 v20, v66, v6
	s_waitcnt lgkmcnt(0)
; DI unsigned f2bf(float f) { unsigned u = __builtin_bit_cast(unsigned, f); return (u + 0x7fffu + ((u >> 16) & 1u)) >> 16; }
; DI float shx(float v, int o, int lane) { return __int_as_float(__builtin_amdgcn_ds_bpermute((lane ^ o) << 2, __float_as_int(v))); }
; DI int crow(int i, int hh) { return (i & 3) + 8 * (i >> 2) + 4 * hh; }
; DI void attn_item(CArgs& a, LAS unsigned char* lds, int l, int b, int h, int qb, int tid_, int wave, int lane_) {
;     ...
;     for (int i = 0; i < 16; ++i) { const float inv = scr[crow(i, hh)]; float s = 0.f;
; #pragma unroll
;         for (int vt = 0; vt < 4; ++vt) { o[vt][i] *= inv; s += o[vt][i] * o[vt][i]; }
;         s += shx(s, 1, lane); s += shx(s, 2, lane); s += shx(s, 4, lane); s += shx(s, 8, lane); s += shx(s, 16, lane);
;         const float rs = rsqrtf(s * (1.f / 128.f) + EPS);
; #pragma unroll
;         for (int vt = 0; vt < 4; ++vt) { const int col = h * 128 + 32 * vt + r; mix[(trow0 + crow(i, hh)) * DM + 1024 + col] = (bf16_t)f2bf(o[vt][i] * rs * a.in[I_MIXG][l * DM + 1024 + col]); } }
	v_pk_add_f32 v[6:7], v[6:7], v[20:21]
	s_nop 0
	v_pk_fma_f32 v[6:7], v[6:7], s[78:79], v[16:17] op_sel_hi:[1,0,0]
	s_nop 0
	v_mul_f32_e32 v20, 0x4b800000, v7
	v_cmp_gt_f32_e64 s[6:7], s64, v7
	v_cmp_gt_f32_e32 vcc, s64, v6
	s_nop 0
	v_cndmask_b32_e64 v7, v7, v20, s[6:7]
	v_rsq_f32_e32 v7, v7
	s_nop 0
	v_mul_f32_e32 v20, 0x45800000, v7
	v_cndmask_b32_e64 v7, v7, v20, s[6:7]
	v_mul_f32_e32 v4, v4, v7
	v_mul_f32_e32 v4, v48, v4
	v_bfe_u32 v20, v4, 16, 1
	v_add3_u32 v4, v4, v20, s33
	v_mov_b32_e32 v82, v4
	v_mul_f32_e32 v4, v5, v7
	v_mul_f32_e32 v4, v68, v4
	v_bfe_u32 v5, v4, 16, 1
	v_add3_u32 v4, v4, v5, s33
	s_nop 1
	v_mov_b32_dpp v83, v82 quad_perm:[1,0,3,2] row_mask:0xf bank_mask:0xf
	v_mov_b32_dpp v84, v4 quad_perm:[1,0,3,2] row_mask:0xf bank_mask:0xf
	v_perm_b32 v85, v83, v82, s98
	v_perm_b32 v86, v4, v84, s98
	v_cndmask_b32_e64 v85, v85, v86, s[100:101]
	v_lshl_add_u64 v[88:89], v[22:23], 0, v[90:91]
	global_store_dword v[88:89], v85, off
	v_mul_f32_e32 v4, v19, v7
	v_mul_f32_e32 v4, v70, v4
	v_bfe_u32 v5, v4, 16, 1
	v_add3_u32 v4, v4, v5, s33
	v_mov_b32_e32 v82, v4
	v_mul_f32_e32 v4, v18, v7
	v_mul_f32_e32 v4, v69, v4
	v_bfe_u32 v5, v4, 16, 1
	v_add3_u32 v4, v4, v5, s33
	s_nop 1
	v_mov_b32_dpp v83, v82 quad_perm:[1,0,3,2] row_mask:0xf bank_mask:0xf
	v_mov_b32_dpp v84, v4 quad_perm:[1,0,3,2] row_mask:0xf bank_mask:0xf
	v_perm_b32 v85, v83, v82, s98
	v_perm_b32 v86, v4, v84, s98
	v_cndmask_b32_e64 v85, v85, v86, s[100:101]
	v_lshl_add_u64 v[88:89], v[22:23], 0, v[90:91]
	global_store_dword v[88:89], v85, off offset:128
	v_mul_f32_e32 v4, 0x4b800000, v6
	v_cndmask_b32_e32 v4, v6, v4, vcc
	v_rsq_f32_e32 v4, v4
	v_or_b32_e32 v18, 18, v64
	v_mov_b32_e32 v19, s1
	v_lshlrev_b64 v[18:19], 12, v[18:19]
	v_mul_f32_e32 v5, 0x45800000, v4
	v_cndmask_b32_e32 v6, v4, v5, vcc
	v_or_b32_e32 v4, 17, v64
	v_mov_b32_e32 v5, s1
	v_mul_f32_e32 v7, v8, v6
	v_lshlrev_b64 v[4:5], 12, v[4:5]
	v_mul_f32_e32 v7, v48, v7
	v_lshl_add_u64 v[4:5], s[12:13], 0, v[4:5]
	v_bfe_u32 v8, v7, 16, 1
	v_add3_u32 v7, v7, v8, s33
	v_lshl_add_u64 v[4:5], v[4:5], 0, v[80:81]
	v_mov_b32_e32 v82, v7
	v_mul_f32_e32 v7, v9, v6
	v_mul_f32_e32 v7, v68, v7
	v_bfe_u32 v8, v7, 16, 1
	v_mul_f32_e32 v1, v1, v6
	v_add3_u32 v7, v7, v8, s33
	v_mul_f32_e32 v1, v70, v1
	s_nop 1
	v_mov_b32_dpp v83, v82 quad_perm:[1,0,3,2] row_mask:0xf bank_mask:0xf
	v_mov_b32_dpp v84, v7 quad_perm:[1,0,3,2] row_mask:0xf bank_mask:0xf
	v_perm_b32 v85, v83, v82, s98
	v_perm_b32 v86, v7, v84, s98
	v_cndmask_b32_e64 v85, v85, v86, s[100:101]
	v_lshl_add_u64 v[88:89], v[4:5], 0, v[90:91]
	global_store_dword v[88:89], v85, off
	v_bfe_u32 v7, v1, 16, 1
	v_mul_f32_e32 v0, v0, v6
	v_add3_u32 v1, v1, v7, s33
	v_mul_f32_e32 v0, v69, v0
	v_mov_b32_e32 v82, v1
	v_bfe_u32 v1, v0, 16, 1
	v_add3_u32 v0, v0, v1, s33
	s_nop 1
	v_mov_b32_dpp v83, v82 quad_perm:[1,0,3,2] row_mask:0xf bank_mask:0xf
	v_mov_b32_dpp v84, v0 quad_perm:[1,0,3,2] row_mask:0xf bank_mask:0xf
	v_perm_b32 v85, v83, v82, s98
	v_perm_b32 v86, v0, v84, s98
	v_cndmask_b32_e64 v85, v85, v86, s[100:101]
	v_lshl_add_u64 v[88:89], v[4:5], 0, v[90:91]
	global_store_dword v[88:89], v85, off offset:128
	v_mov_b32_e32 v0, v10
	v_mov_b32_e32 v1, v26
	v_mov_b32_e32 v6, v58
	v_mov_b32_e32 v7, v42
	v_pk_mul_f32 v[0:1], v[0:1], v[2:3] op_sel_hi:[1,0]
	v_pk_mul_f32 v[6:7], v[6:7], v[2:3] op_sel_hi:[1,0]
	v_mov_b32_e32 v26, v11
	v_mov_b32_e32 v2, v3
	v_pk_mul_f32 v[10:11], v[26:27], v[2:3] op_sel_hi:[1,0]
	v_mov_b32_e32 v42, v59
	v_pk_mul_f32 v[4:5], v[0:1], v[0:1]
	v_pk_mul_f32 v[20:21], v[10:11], v[10:11]
	v_pk_mul_f32 v[2:3], v[42:43], v[2:3] op_sel_hi:[1,0]
	v_pk_mul_f32 v[8:9], v[6:7], v[6:7]
	v_pk_mul_f32 v[22:23], v[2:3], v[2:3]
	v_mov_b32_e32 v24, v20
	v_mov_b32_e32 v25, v4
	v_mov_b32_e32 v4, v21
	v_pk_add_f32 v[4:5], v[24:25], v[4:5]
	v_mov_b32_e32 v20, v23
	v_mov_b32_e32 v21, v9
	v_pk_add_f32 v[4:5], v[20:21], v[4:5]
	v_mov_b32_e32 v23, v8
	v_pk_add_f32 v[4:5], v[22:23], v[4:5]
	ds_bpermute_b32 v9, v73, v5
	ds_bpermute_b32 v8, v73, v4
	v_lshl_add_u64 v[18:19], s[12:13], 0, v[18:19]
	v_lshl_add_u64 v[18:19], v[18:19], 0, v[80:81]
	v_mov_b32_e32 v42, v81
	v_mov_b32_e32 v43, v81
	s_waitcnt lgkmcnt(0)
	v_pk_add_f32 v[4:5], v[4:5], v[8:9]
	ds_bpermute_b32 v9, v72, v5
	ds_bpermute_b32 v8, v72, v4
	v_mov_b32_e32 v58, v81
	v_mov_b32_e32 v59, v81
	s_waitcnt lgkmcnt(0)
	v_pk_add_f32 v[4:5], v[4:5], v[8:9]
	ds_bpermute_b32 v9, v71, v5
	ds_bpermute_b32 v8, v71, v4
	s_waitcnt lgkmcnt(0)
	v_pk_add_f32 v[4:5], v[4:5], v[8:9]
	ds_bpermute_b32 v9, v67, v5
	ds_bpermute_b32 v8, v67, v4
	s_waitcnt lgkmcnt(0)
	v_pk_add_f32 v[4:5], v[4:5], v[8:9]
	ds_bpermute_b32 v9, v66, v5
	ds_bpermute_b32 v8, v66, v4
	s_waitcnt lgkmcnt(0)
; DI unsigned f2bf(float f) { unsigned u = __builtin_bit_cast(unsigned, f); return (u + 0x7fffu + ((u >> 16) & 1u)) >> 16; }
; DI float shx(float v, int o, int lane) { return __int_as_float(__builtin_amdgcn_ds_bpermute((lane ^ o) << 2, __float_as_int(v))); }
; DI int crow(int i, int hh) { return (i & 3) + 8 * (i >> 2) + 4 * hh; }
; DI void attn_item(CArgs& a, LAS unsigned char* lds, int l, int b, int h, int qb, int tid_, int wave, int lane_) {
;     ...
;     for (int i = 0; i < 16; ++i) { const float inv = scr[crow(i, hh)]; float s = 0.f;
; #pragma unroll
;         for (int vt = 0; vt < 4; ++vt) { o[vt][i] *= inv; s += o[vt][i] * o[vt][i]; }
;         s += shx(s, 1, lane); s += shx(s, 2, lane); s += shx(s, 4, lane); s += shx(s, 8, lane); s += shx(s, 16, lane);
;         const float rs = rsqrtf(s * (1.f / 128.f) + EPS);
; #pragma unroll
;         for (int vt = 0; vt < 4; ++vt) { const int col = h * 128 + 32 * vt + r; mix[(trow0 + crow(i, hh)) * DM + 1024 + col] = (bf16_t)f2bf(o[vt][i] * rs * a.in[I_MIXG][l * DM + 1024 + col]); } }
	v_pk_add_f32 v[4:5], v[4:5], v[8:9]
	s_nop 0
	v_pk_fma_f32 v[4:5], v[4:5], s[78:79], v[16:17] op_sel_hi:[1,0,0]
	v_mov_b32_e32 v9, v44
	v_mul_f32_e32 v8, 0x4b800000, v5
	v_cmp_gt_f32_e64 s[6:7], s64, v5
	v_cmp_gt_f32_e32 vcc, s64, v4
	v_mov_b32_e32 v44, v61
	v_cndmask_b32_e64 v5, v5, v8, s[6:7]
	v_rsq_f32_e32 v5, v5
	v_mov_b32_e32 v61, v81
	v_mul_f32_e32 v8, 0x45800000, v5
	v_cndmask_b32_e64 v5, v5, v8, s[6:7]
	v_mul_f32_e32 v0, v0, v5
	v_mul_f32_e32 v0, v48, v0
	v_bfe_u32 v8, v0, 16, 1
	v_add3_u32 v0, v0, v8, s33
	v_mov_b32_e32 v82, v0
	v_mul_f32_e32 v0, v1, v5
	v_mul_f32_e32 v0, v68, v0
	v_bfe_u32 v1, v0, 16, 1
	v_add3_u32 v0, v0, v1, s33
	s_nop 1
	v_mov_b32_dpp v83, v82 quad_perm:[1,0,3,2] row_mask:0xf bank_mask:0xf
	v_mov_b32_dpp v84, v0 quad_perm:[1,0,3,2] row_mask:0xf bank_mask:0xf
	v_perm_b32 v85, v83, v82, s98
	v_perm_b32 v86, v0, v84, s98
	v_cndmask_b32_e64 v85, v85, v86, s[100:101]
	v_lshl_add_u64 v[88:89], v[18:19], 0, v[90:91]
	global_store_dword v[88:89], v85, off
	v_mul_f32_e32 v0, v7, v5
	v_mul_f32_e32 v0, v70, v0
	v_bfe_u32 v1, v0, 16, 1
	v_add3_u32 v0, v0, v1, s33
	v_mov_b32_e32 v82, v0
	v_mul_f32_e32 v0, v6, v5
	v_mul_f32_e32 v0, v69, v0
	v_bfe_u32 v1, v0, 16, 1
	v_add3_u32 v0, v0, v1, s33
	s_nop 1
	v_mov_b32_dpp v83, v82 quad_perm:[1,0,3,2] row_mask:0xf bank_mask:0xf
	v_mov_b32_dpp v84, v0 quad_perm:[1,0,3,2] row_mask:0xf bank_mask:0xf
	v_perm_b32 v85, v83, v82, s98
	v_perm_b32 v86, v0, v84, s98
	v_cndmask_b32_e64 v85, v85, v86, s[100:101]
	v_lshl_add_u64 v[88:89], v[18:19], 0, v[90:91]
	global_store_dword v[88:89], v85, off offset:128
	v_mul_f32_e32 v0, 0x4b800000, v4
	v_cndmask_b32_e32 v0, v4, v0, vcc
	v_rsq_f32_e32 v0, v0
	v_mov_b32_e32 v8, v60
	v_or_b32_e32 v18, 24, v64
	v_mov_b32_e32 v19, s1
	v_mul_f32_e32 v1, 0x45800000, v0
	v_cndmask_b32_e32 v4, v0, v1, vcc
	v_or_b32_e32 v0, 19, v64
	v_mov_b32_e32 v1, s1
	v_mul_f32_e32 v5, v10, v4
	v_lshlrev_b64 v[0:1], 12, v[0:1]
	v_mul_f32_e32 v5, v48, v5
	v_lshl_add_u64 v[0:1], s[12:13], 0, v[0:1]
	v_bfe_u32 v6, v5, 16, 1
	v_add3_u32 v5, v5, v6, s33
	v_lshl_add_u64 v[0:1], v[0:1], 0, v[80:81]
	v_mov_b32_e32 v82, v5
	v_mul_f32_e32 v5, v11, v4
	v_mul_f32_e32 v5, v68, v5
	v_bfe_u32 v6, v5, 16, 1
	v_mul_f32_e32 v3, v3, v4
	v_add3_u32 v5, v5, v6, s33
	v_mul_f32_e32 v3, v70, v3
	s_nop 1
	v_mov_b32_dpp v83, v82 quad_perm:[1,0,3,2] row_mask:0xf bank_mask:0xf
	v_mov_b32_dpp v84, v5 quad_perm:[1,0,3,2] row_mask:0xf bank_mask:0xf
	v_perm_b32 v85, v83, v82, s98
	v_perm_b32 v86, v5, v84, s98
	v_cndmask_b32_e64 v85, v85, v86, s[100:101]
	v_lshl_add_u64 v[88:89], v[0:1], 0, v[90:91]
	global_store_dword v[88:89], v85, off
	v_bfe_u32 v5, v3, 16, 1
	v_mul_f32_e32 v2, v2, v4
	v_add3_u32 v3, v3, v5, s33
	v_mul_f32_e32 v2, v69, v2
	v_mov_b32_e32 v82, v3
	v_bfe_u32 v3, v2, 16, 1
	v_add3_u32 v2, v2, v3, s33
	s_nop 1
	v_mov_b32_dpp v83, v82 quad_perm:[1,0,3,2] row_mask:0xf bank_mask:0xf
	v_mov_b32_dpp v84, v2 quad_perm:[1,0,3,2] row_mask:0xf bank_mask:0xf
	v_perm_b32 v85, v83, v82, s98
	v_perm_b32 v86, v2, v84, s98
	v_cndmask_b32_e64 v85, v85, v86, s[100:101]
	v_lshl_add_u64 v[88:89], v[0:1], 0, v[90:91]
	global_store_dword v[88:89], v85, off offset:128
	ds_read_b128 v[0:3], v74 offset:96
	v_mov_b32_e32 v4, v12
	v_mov_b32_e32 v5, v28
	v_mov_b32_e32 v28, v13
	v_lshlrev_b64 v[18:19], 12, v[18:19]
	s_waitcnt lgkmcnt(0)
	v_pk_mul_f32 v[4:5], v[4:5], v[0:1] op_sel_hi:[1,0]
	v_pk_mul_f32 v[12:13], v[28:29], v[0:1] op_sel:[0,1]
	v_pk_mul_f32 v[6:7], v[4:5], v[4:5]
	v_pk_mul_f32 v[8:9], v[8:9], v[0:1] op_sel_hi:[1,0]
	v_pk_mul_f32 v[20:21], v[12:13], v[12:13]
	v_pk_mul_f32 v[0:1], v[44:45], v[0:1] op_sel:[0,1]
	v_pk_mul_f32 v[10:11], v[8:9], v[8:9]
	v_pk_mul_f32 v[22:23], v[0:1], v[0:1]
	v_mov_b32_e32 v24, v20
	v_mov_b32_e32 v25, v6
	v_mov_b32_e32 v6, v21
	v_pk_add_f32 v[6:7], v[24:25], v[6:7]
	v_mov_b32_e32 v20, v23
	v_mov_b32_e32 v21, v11
	v_pk_add_f32 v[6:7], v[20:21], v[6:7]
	v_mov_b32_e32 v23, v10
	v_pk_add_f32 v[6:7], v[22:23], v[6:7]
	ds_bpermute_b32 v11, v73, v7
	ds_bpermute_b32 v10, v73, v6
	v_lshl_add_u64 v[18:19], s[12:13], 0, v[18:19]
	v_lshl_add_u64 v[18:19], v[18:19], 0, v[80:81]
	v_mov_b32_e32 v44, v81
	v_mov_b32_e32 v45, v81
	s_waitcnt lgkmcnt(0)
	v_pk_add_f32 v[6:7], v[6:7], v[10:11]
	ds_bpermute_b32 v11, v72, v7
	ds_bpermute_b32 v10, v72, v6
	v_mov_b32_e32 v60, v81
	s_waitcnt lgkmcnt(0)
	v_pk_add_f32 v[6:7], v[6:7], v[10:11]
	ds_bpermute_b32 v11, v71, v7
	ds_bpermute_b32 v10, v71, v6
	s_waitcnt lgkmcnt(0)
	v_pk_add_f32 v[6:7], v[6:7], v[10:11]
	ds_bpermute_b32 v11, v67, v7
	ds_bpermute_b32 v10, v67, v6
	s_waitcnt lgkmcnt(0)
	v_pk_add_f32 v[6:7], v[6:7], v[10:11]
	ds_bpermute_b32 v11, v66, v7
	ds_bpermute_b32 v10, v66, v6
	s_waitcnt lgkmcnt(0)
; DI unsigned f2bf(float f) { unsigned u = __builtin_bit_cast(unsigned, f); return (u + 0x7fffu + ((u >> 16) & 1u)) >> 16; }
; DI float shx(float v, int o, int lane) { return __int_as_float(__builtin_amdgcn_ds_bpermute((lane ^ o) << 2, __float_as_int(v))); }
; DI int crow(int i, int hh) { return (i & 3) + 8 * (i >> 2) + 4 * hh; }
; DI void attn_item(CArgs& a, LAS unsigned char* lds, int l, int b, int h, int qb, int tid_, int wave, int lane_) {
;     ...
;     for (int i = 0; i < 16; ++i) { const float inv = scr[crow(i, hh)]; float s = 0.f;
; #pragma unroll
;         for (int vt = 0; vt < 4; ++vt) { o[vt][i] *= inv; s += o[vt][i] * o[vt][i]; }
;         s += shx(s, 1, lane); s += shx(s, 2, lane); s += shx(s, 4, lane); s += shx(s, 8, lane); s += shx(s, 16, lane);
;         const float rs = rsqrtf(s * (1.f / 128.f) + EPS);
; #pragma unroll
;         for (int vt = 0; vt < 4; ++vt) { const int col = h * 128 + 32 * vt + r; mix[(trow0 + crow(i, hh)) * DM + 1024 + col] = (bf16_t)f2bf(o[vt][i] * rs * a.in[I_MIXG][l * DM + 1024 + col]); } }
	v_pk_add_f32 v[6:7], v[6:7], v[10:11]
	s_nop 0
	v_pk_fma_f32 v[6:7], v[6:7], s[78:79], v[16:17] op_sel_hi:[1,0,0]
	v_mov_b32_e32 v11, s1
	v_mul_f32_e32 v10, 0x4b800000, v7
	v_cmp_gt_f32_e64 s[6:7], s64, v7
	v_cmp_gt_f32_e32 vcc, s64, v6
	s_nop 0
	v_cndmask_b32_e64 v7, v7, v10, s[6:7]
	v_rsq_f32_e32 v7, v7
	s_nop 0
	v_mul_f32_e32 v10, 0x45800000, v7
	v_cndmask_b32_e64 v7, v7, v10, s[6:7]
	v_mul_f32_e32 v4, v4, v7
	v_mul_f32_e32 v4, v48, v4
	v_bfe_u32 v10, v4, 16, 1
	v_add3_u32 v4, v4, v10, s33
	v_mov_b32_e32 v82, v4
	v_mul_f32_e32 v4, v5, v7
	v_mul_f32_e32 v4, v68, v4
	v_bfe_u32 v5, v4, 16, 1
	v_add3_u32 v4, v4, v5, s33
	s_nop 1
	v_mov_b32_dpp v83, v82 quad_perm:[1,0,3,2] row_mask:0xf bank_mask:0xf
	v_mov_b32_dpp v84, v4 quad_perm:[1,0,3,2] row_mask:0xf bank_mask:0xf
	v_perm_b32 v85, v83, v82, s98
	v_perm_b32 v86, v4, v84, s98
	v_cndmask_b32_e64 v85, v85, v86, s[100:101]
	v_lshl_add_u64 v[88:89], v[18:19], 0, v[90:91]
	global_store_dword v[88:89], v85, off
	v_mul_f32_e32 v4, v9, v7
	v_mul_f32_e32 v4, v70, v4
	v_bfe_u32 v5, v4, 16, 1
	v_add3_u32 v4, v4, v5, s33
	v_mov_b32_e32 v82, v4
	v_mul_f32_e32 v4, v8, v7
	v_mul_f32_e32 v4, v69, v4
	v_bfe_u32 v5, v4, 16, 1
	v_add3_u32 v4, v4, v5, s33
	s_nop 1
	v_mov_b32_dpp v83, v82 quad_perm:[1,0,3,2] row_mask:0xf bank_mask:0xf
	v_mov_b32_dpp v84, v4 quad_perm:[1,0,3,2] row_mask:0xf bank_mask:0xf
	v_perm_b32 v85, v83, v82, s98
	v_perm_b32 v86, v4, v84, s98
	v_cndmask_b32_e64 v85, v85, v86, s[100:101]
	v_lshl_add_u64 v[88:89], v[18:19], 0, v[90:91]
	global_store_dword v[88:89], v85, off offset:128
	v_mul_f32_e32 v4, 0x4b800000, v6
	v_cndmask_b32_e32 v4, v6, v4, vcc
	v_rsq_f32_e32 v4, v4
	v_or_b32_e32 v10, 26, v64
	v_lshlrev_b64 v[10:11], 12, v[10:11]
	v_lshl_add_u64 v[10:11], s[12:13], 0, v[10:11]
	v_mul_f32_e32 v5, 0x45800000, v4
	v_cndmask_b32_e32 v6, v4, v5, vcc
	v_or_b32_e32 v4, 25, v64
	v_mov_b32_e32 v5, s1
	v_mul_f32_e32 v7, v12, v6
	v_lshlrev_b64 v[4:5], 12, v[4:5]
	v_mul_f32_e32 v7, v48, v7
	v_lshl_add_u64 v[4:5], s[12:13], 0, v[4:5]
	v_bfe_u32 v8, v7, 16, 1
	v_add3_u32 v7, v7, v8, s33
	v_lshl_add_u64 v[4:5], v[4:5], 0, v[80:81]
	v_mov_b32_e32 v82, v7
	v_mul_f32_e32 v7, v13, v6
	v_mul_f32_e32 v7, v68, v7
	v_bfe_u32 v8, v7, 16, 1
	v_mul_f32_e32 v1, v1, v6
	v_add3_u32 v7, v7, v8, s33
	v_mul_f32_e32 v1, v70, v1
	s_nop 1
	v_mov_b32_dpp v83, v82 quad_perm:[1,0,3,2] row_mask:0xf bank_mask:0xf
	v_mov_b32_dpp v84, v7 quad_perm:[1,0,3,2] row_mask:0xf bank_mask:0xf
	v_perm_b32 v85, v83, v82, s98
	v_perm_b32 v86, v7, v84, s98
	v_cndmask_b32_e64 v85, v85, v86, s[100:101]
	v_lshl_add_u64 v[88:89], v[4:5], 0, v[90:91]
	global_store_dword v[88:89], v85, off
	v_bfe_u32 v7, v1, 16, 1
	v_mul_f32_e32 v0, v0, v6
	v_add3_u32 v1, v1, v7, s33
	v_mul_f32_e32 v0, v69, v0
	v_mov_b32_e32 v82, v1
	v_bfe_u32 v1, v0, 16, 1
	v_add3_u32 v0, v0, v1, s33
	s_nop 1
	v_mov_b32_dpp v83, v82 quad_perm:[1,0,3,2] row_mask:0xf bank_mask:0xf
	v_mov_b32_dpp v84, v0 quad_perm:[1,0,3,2] row_mask:0xf bank_mask:0xf
	v_perm_b32 v85, v83, v82, s98
	v_perm_b32 v86, v0, v84, s98
	v_cndmask_b32_e64 v85, v85, v86, s[100:101]
	v_lshl_add_u64 v[88:89], v[4:5], 0, v[90:91]
	global_store_dword v[88:89], v85, off offset:128
	v_mov_b32_e32 v0, v14
	v_mov_b32_e32 v1, v30
	v_mov_b32_e32 v6, v62
	v_mov_b32_e32 v7, v46
	v_pk_mul_f32 v[0:1], v[0:1], v[2:3] op_sel_hi:[1,0]
	v_pk_mul_f32 v[6:7], v[6:7], v[2:3] op_sel_hi:[1,0]
	v_mov_b32_e32 v30, v15
	v_mov_b32_e32 v2, v3
	v_pk_mul_f32 v[12:13], v[30:31], v[2:3] op_sel_hi:[1,0]
	v_mov_b32_e32 v46, v63
	v_pk_mul_f32 v[4:5], v[0:1], v[0:1]
	v_pk_mul_f32 v[14:15], v[12:13], v[12:13]
	v_pk_mul_f32 v[2:3], v[46:47], v[2:3] op_sel_hi:[1,0]
	v_pk_mul_f32 v[8:9], v[6:7], v[6:7]
	v_pk_mul_f32 v[18:19], v[2:3], v[2:3]
	v_mov_b32_e32 v20, v14
	v_mov_b32_e32 v21, v4
	v_mov_b32_e32 v4, v15
	v_pk_add_f32 v[4:5], v[20:21], v[4:5]
	v_mov_b32_e32 v14, v19
	v_mov_b32_e32 v15, v9
	v_pk_add_f32 v[4:5], v[14:15], v[4:5]
	v_mov_b32_e32 v19, v8
	v_pk_add_f32 v[4:5], v[18:19], v[4:5]
	ds_bpermute_b32 v9, v73, v5
	ds_bpermute_b32 v8, v73, v4
	v_lshl_add_u64 v[10:11], v[10:11], 0, v[80:81]
	v_or_b32_e32 v64, 27, v64
	s_add_i32 s1, s5, s26
	v_mov_b32_e32 v46, v81
	s_waitcnt lgkmcnt(0)
	v_pk_add_f32 v[4:5], v[4:5], v[8:9]
	ds_bpermute_b32 v9, v72, v5
	ds_bpermute_b32 v8, v72, v4
	v_mov_b32_e32 v47, v81
	v_mov_b32_e32 v62, v81
	v_mov_b32_e32 v63, v81
	v_mov_b32_e32 v73, v81
	s_waitcnt lgkmcnt(0)
	v_pk_add_f32 v[4:5], v[4:5], v[8:9]
	ds_bpermute_b32 v9, v71, v5
	ds_bpermute_b32 v8, v71, v4
	v_mov_b32_e32 v71, v81
	s_waitcnt lgkmcnt(0)
	v_pk_add_f32 v[4:5], v[4:5], v[8:9]
	ds_bpermute_b32 v9, v67, v5
	ds_bpermute_b32 v8, v67, v4
	v_mov_b32_e32 v67, v81
	s_waitcnt lgkmcnt(0)
	v_pk_add_f32 v[4:5], v[4:5], v[8:9]
	ds_bpermute_b32 v9, v66, v5
	ds_bpermute_b32 v8, v66, v4
	s_waitcnt lgkmcnt(0)
; #define LAS __attribute__((address_space(3)))
; DI unsigned f2bf(float f) { unsigned u = __builtin_bit_cast(unsigned, f); return (u + 0x7fffu + ((u >> 16) & 1u)) >> 16; }
; DI void unpack8(const u32x4 w, float (&f)[8]) { f[0] = bflo(w.x); f[1] = bfhi(w.x); f[2] = bflo(w.y); f[3] = bfhi(w.y); f[4] = bflo(w.z); f[5] = bfhi(w.z); f[6] = bflo(w.w); f[7] = bfhi(w.w); }
; DI u32x4 pack8f(const float (&f)[8]) { u32x4 w; w.x = pk2(f[0], f[1]); w.y = pk2(f[2], f[3]); w.z = pk2(f[4], f[5]); w.w = pk2(f[6], f[7]); return w; }
; DI void attn_item(CArgs& a, LAS unsigned char* lds, int l, int b, int h, int qb, int tid_, int wave, int lane_) {
;     int tid = tid_; asm volatile("" : "+v"(tid)); const int lane = tid & 63;
;     LAS float* scr = (LAS float*)(lds + AT_SCR) + wave * 64;
;     const int r = lane & 31, hh = lane >> 5;
;     const int qloc = qb * 256 + wave * 32 + r; const size_t tq = (size_t)b * S_ + qloc;
;     AttnOff F;
; #pragma unroll
;     for (int i = 0; i < 2; ++i) { const int ck = tid + 512 * i, row = ck >> 4, cc = ck & 15; F.gk[i] = (unsigned)(row * 512 + 8 * cc) * 2u; }
;     { const int row = tid >> 3, cc = tid & 7; F.gr = (unsigned)(row * 64 + 8 * cc) * 2u; }
; #pragma unroll
;     for (int i = 0; i < 2; ++i) { const int cv = tid + 512 * i, v = cv >> 3, cc = cv & 7; F.gv[i] = (unsigned)(v * T_ + 8 * cc) * 2u; }
;     bf16x8 qf[12];
;     { const bf16_t* qp = (const bf16_t*)(a.ws + B_QB) + tq * 768 + h * 192; const float sc = 0.07216878364870322f * 1.4426950408889634f;
; #pragma unroll
;       for (int ks = 0; ks < 8; ++ks) { float f[8]; unpack8(*(const u32x4*)(qp + 16 * ks + 8 * hh), f);
; #pragma unroll
;           for (int e = 0; e < 8; ++e) f[e] *= sc;
;           qf[ks] = __builtin_bit_cast(bf16x8, pack8f(f)); }
;     ...
;     for (int i = 0; i < 16; ++i) { const float inv = scr[crow(i, hh)]; float s = 0.f;
; #pragma unroll
;         for (int vt = 0; vt < 4; ++vt) { o[vt][i] *= inv; s += o[vt][i] * o[vt][i]; }
;         s += shx(s, 1, lane); s += shx(s, 2, lane); s += shx(s, 4, lane); s += shx(s, 8, lane); s += shx(s, 16, lane);
;         const float rs = rsqrtf(s * (1.f / 128.f) + EPS);
; #pragma unroll
;         for (int vt = 0; vt < 4; ++vt) { const int col = h * 128 + 32 * vt + r; mix[(trow0 + crow(i, hh)) * DM + 1024 + col] = (bf16_t)f2bf(o[vt][i] * rs * a.in[I_MIXG][l * DM + 1024 + col]); } }
	v_pk_add_f32 v[4:5], v[4:5], v[8:9]
	s_nop 0
	v_pk_fma_f32 v[4:5], v[4:5], s[78:79], v[16:17] op_sel_hi:[1,0,0]
	s_nop 0
	v_mul_f32_e32 v8, 0x4b800000, v5
	v_cmp_gt_f32_e64 s[6:7], s64, v5
	v_cmp_gt_f32_e32 vcc, s64, v4
	s_nop 0
	v_cndmask_b32_e64 v5, v5, v8, s[6:7]
	v_rsq_f32_e32 v5, v5
	s_nop 0
	v_mul_f32_e32 v8, 0x45800000, v5
	v_cndmask_b32_e64 v5, v5, v8, s[6:7]
	v_mul_f32_e32 v0, v0, v5
	v_mul_f32_e32 v0, v48, v0
	v_bfe_u32 v8, v0, 16, 1
	v_add3_u32 v0, v0, v8, s33
	v_mov_b32_e32 v82, v0
	v_mul_f32_e32 v0, v1, v5
	v_mul_f32_e32 v0, v68, v0
	v_bfe_u32 v1, v0, 16, 1
	v_add3_u32 v0, v0, v1, s33
	s_nop 1
	v_mov_b32_dpp v83, v82 quad_perm:[1,0,3,2] row_mask:0xf bank_mask:0xf
	v_mov_b32_dpp v84, v0 quad_perm:[1,0,3,2] row_mask:0xf bank_mask:0xf
	v_perm_b32 v85, v83, v82, s98
	v_perm_b32 v86, v0, v84, s98
	v_cndmask_b32_e64 v85, v85, v86, s[100:101]
	v_lshl_add_u64 v[88:89], v[10:11], 0, v[90:91]
	global_store_dword v[88:89], v85, off
	v_mul_f32_e32 v0, v7, v5
	v_mul_f32_e32 v0, v70, v0
	v_bfe_u32 v1, v0, 16, 1
	v_add3_u32 v0, v0, v1, s33
	v_mov_b32_e32 v82, v0
	v_mul_f32_e32 v0, v6, v5
	v_mul_f32_e32 v0, v69, v0
	v_bfe_u32 v1, v0, 16, 1
	v_add3_u32 v0, v0, v1, s33
	s_nop 1
	v_mov_b32_dpp v83, v82 quad_perm:[1,0,3,2] row_mask:0xf bank_mask:0xf
	v_mov_b32_dpp v84, v0 quad_perm:[1,0,3,2] row_mask:0xf bank_mask:0xf
	v_perm_b32 v85, v83, v82, s98
	v_perm_b32 v86, v0, v84, s98
	v_cndmask_b32_e64 v85, v85, v86, s[100:101]
	v_lshl_add_u64 v[88:89], v[10:11], 0, v[90:91]
	global_store_dword v[88:89], v85, off offset:128
	v_mul_f32_e32 v0, 0x4b800000, v4
	v_cndmask_b32_e32 v0, v4, v0, vcc
	v_rsq_f32_e32 v0, v0
	s_nop 0
	v_mul_f32_e32 v1, 0x45800000, v0
	v_cndmask_b32_e32 v4, v0, v1, vcc
	v_mul_f32_e32 v5, v12, v4
	v_lshlrev_b64 v[0:1], 12, v[64:65]
	v_mul_f32_e32 v5, v48, v5
	v_lshl_add_u64 v[0:1], s[12:13], 0, v[0:1]
	v_bfe_u32 v6, v5, 16, 1
	v_add3_u32 v5, v5, v6, s33
	v_lshl_add_u64 v[0:1], v[0:1], 0, v[80:81]
	v_mov_b32_e32 v82, v5
	v_mul_f32_e32 v5, v13, v4
	v_mul_f32_e32 v5, v68, v5
	v_bfe_u32 v6, v5, 16, 1
	v_mul_f32_e32 v3, v3, v4
	v_add3_u32 v5, v5, v6, s33
	v_mul_f32_e32 v3, v70, v3
	s_nop 1
	v_mov_b32_dpp v83, v82 quad_perm:[1,0,3,2] row_mask:0xf bank_mask:0xf
	v_mov_b32_dpp v84, v5 quad_perm:[1,0,3,2] row_mask:0xf bank_mask:0xf
	v_perm_b32 v85, v83, v82, s98
	v_perm_b32 v86, v5, v84, s98
	v_cndmask_b32_e64 v85, v85, v86, s[100:101]
	v_lshl_add_u64 v[88:89], v[0:1], 0, v[90:91]
	global_store_dword v[88:89], v85, off
	v_bfe_u32 v5, v3, 16, 1
	v_mul_f32_e32 v2, v2, v4
	v_add3_u32 v3, v3, v5, s33
	v_mul_f32_e32 v2, v69, v2
	v_mov_b32_e32 v82, v3
	v_bfe_u32 v3, v2, 16, 1
	v_add3_u32 v2, v2, v3, s33
	s_nop 1
	v_mov_b32_dpp v83, v82 quad_perm:[1,0,3,2] row_mask:0xf bank_mask:0xf
	v_mov_b32_dpp v84, v2 quad_perm:[1,0,3,2] row_mask:0xf bank_mask:0xf
	v_perm_b32 v85, v83, v82, s98
	v_perm_b32 v86, v2, v84, s98
	v_cndmask_b32_e64 v85, v85, v86, s[100:101]
	v_lshl_add_u64 v[88:89], v[0:1], 0, v[90:91]
	global_store_dword v[88:89], v85, off offset:128
	s_waitcnt lgkmcnt(0)
	v_mov_b64_e32 v[2:3], s[10:11]
	v_and_b32_e32 v169, 31, v77
	v_lshlrev_b32_e32 v78, 3, v77
	v_or_b32_e32 v174, s1, v169
	v_lshlrev_b32_e32 v0, 5, v77
	v_and_b32_e32 v188, 0x78, v78
	s_mov_b32 s1, 0x7ffffe00
	v_and_or_b32 v1, v0, s1, v188
	v_add_u32_e32 v0, 0x4000, v0
	v_and_or_b32 v0, v0, s1, v188
	v_lshlrev_b32_e32 v66, 1, v0
	v_lshlrev_b32_e32 v0, 12, v77
	v_and_b32_e32 v79, 56, v78
	s_mov_b32 s1, 0x7fff8000
	v_lshlrev_b32_e32 v64, 1, v1
	v_and_or_b32 v1, v0, s1, v79
	v_add_u32_e32 v0, 0x200000, v0
	v_ashrrev_i32_e32 v175, 31, v174
	v_and_or_b32 v0, v0, s1, v79
	v_lshlrev_b32_e32 v70, 1, v1
	v_lshlrev_b32_e32 v72, 1, v0
	v_lshl_add_u64 v[0:1], s[14:15], 0, v[174:175]
	v_mad_u64_u32 v[2:3], s[6:7], v0, s65, v[2:3]
	v_bfe_u32 v76, v77, 5, 1
	v_mad_i32_i24 v3, v1, s65, v3
	v_lshl_add_u64 v[2:3], v[2:3], 0, s[36:37]
	v_lshlrev_b32_e32 v80, 4, v76
	v_lshl_add_u64 v[4:5], v[2:3], 0, v[80:81]
	global_load_dwordx4 v[6:9], v[4:5], off
	s_mov_b32 s36, 0x3dd53b94
	v_lshlrev_b64 v[0:1], 8, v[0:1]
	s_mov_b32 s1, 0x200000
	s_mov_b64 s[6:7], 0x200000
	v_mov_b32_e32 v48, v81
	v_lshlrev_b32_e32 v68, 4, v77
	v_lshrrev_b32_e32 v175, 4, v77
	v_lshl_add_u32 v176, v188, 1, 0
	v_and_b32_e32 v74, 63, v77
	v_and_b32_e32 v78, 48, v78
	v_lshlrev_b32_e32 v192, 1, v78
	v_lshlrev_b32_e32 v191, 1, v79
	v_lshlrev_b32_e32 v75, 3, v76
	v_mov_b32_e32 v65, v81
	v_mov_b32_e32 v69, v81
	v_lshlrev_b32_e32 v196, 2, v74
	v_lshlrev_b32_e32 v195, 2, v76
	v_xor_b32_e32 v198, 0x80, v196
	v_lshl_add_u32 v197, v169, 2, s27
	v_mul_u32_u24_e32 v199, 0x90, v169
	v_mul_u32_u24_e32 v200, 0x110, v169
	v_lshl_add_u64 v[178:179], s[20:21], 0, v[72:73]
	v_lshl_add_u64 v[180:181], s[22:23], 0, v[68:69]
	v_lshl_add_u64 v[182:183], s[38:39], 0, v[64:65]
	v_lshl_add_u64 v[184:185], s[38:39], 0, v[66:67]
	v_lshlrev_b32_e32 v202, 1, v75
	s_waitcnt vmcnt(0)
	v_lshlrev_b32_e32 v2, 16, v6
	v_and_b32_e32 v3, 0xffff0000, v6
	v_lshlrev_b32_e32 v6, 16, v7
	v_and_b32_e32 v7, 0xffff0000, v7
	v_lshlrev_b32_e32 v10, 16, v8
	v_and_b32_e32 v11, 0xffff0000, v8
	v_lshlrev_b32_e32 v8, 16, v9
	v_and_b32_e32 v9, 0xffff0000, v9
	v_pk_mul_f32 v[6:7], v[6:7], s[36:37] op_sel_hi:[1,0]
	v_pk_mul_f32 v[8:9], v[8:9], s[36:37] op_sel_hi:[1,0]
	v_cvt_pk_bf16_f32 v99, v6, v7
	v_cvt_pk_bf16_f32 v101, v8, v9
	global_load_dwordx4 v[6:9], v[4:5], off offset:32
	v_pk_mul_f32 v[2:3], v[2:3], s[36:37] op_sel_hi:[1,0]
	v_pk_mul_f32 v[10:11], v[10:11], s[36:37] op_sel_hi:[1,0]
	v_cvt_pk_bf16_f32 v98, v2, v3
	v_cvt_pk_bf16_f32 v100, v10, v11
	s_waitcnt vmcnt(0)
; DI void unpack8(const u32x4 w, float (&f)[8]) { f[0] = bflo(w.x); f[1] = bfhi(w.x); f[2] = bflo(w.y); f[3] = bfhi(w.y); f[4] = bflo(w.z); f[5] = bfhi(w.z); f[6] = bflo(w.w); f[7] = bfhi(w.w); }
; DI u32x4 pack8f(const float (&f)[8]) { u32x4 w; w.x = pk2(f[0], f[1]); w.y = pk2(f[2], f[3]); w.z = pk2(f[4], f[5]); w.w = pk2(f[6], f[7]); return w; }
; DI void attn_item(CArgs& a, LAS unsigned char* lds, int l, int b, int h, int qb, int tid_, int wave, int lane_) {
;     ...
;     { const bf16_t* qp = (const bf16_t*)(a.ws + B_QB) + tq * 768 + h * 192; const float sc = 0.07216878364870322f * 1.4426950408889634f;
; #pragma unroll
;       for (int ks = 0; ks < 8; ++ks) { float f[8]; unpack8(*(const u32x4*)(qp + 16 * ks + 8 * hh), f);
; #pragma unroll
;           for (int e = 0; e < 8; ++e) f[e] *= sc;
;           qf[ks] = __builtin_bit_cast(bf16x8, pack8f(f)); }
; #pragma unroll
;       for (int ks = 8; ks < 10; ++ks) { float x1[8], x2[8], o1[8], o2[8]; unpack8(*(const u32x4*)(qp + 16 * ks + 8 * hh), x1); unpack8(*(const u32x4*)(qp + 16 * (ks + 2) + 8 * hh), x2);
;           const f32x2* cs = (const f32x2*)(a.ws + WS_ROPE) + tq * 32 + 16 * (ks - 8) + 8 * hh;
; #pragma unroll
;           for (int e = 0; e < 8; ++e) { const f32x2 t = cs[e]; o1[e] = (x1[e] * t.x - x2[e] * t.y) * sc; o2[e] = (x1[e] * t.y + x2[e] * t.x) * sc; }
;           qf[ks] = __builtin_bit_cast(bf16x8, pack8f(o1)); qf[ks + 2] = __builtin_bit_cast(bf16x8, pack8f(o2)); } }
	v_lshlrev_b32_e32 v2, 16, v6
	v_and_b32_e32 v3, 0xffff0000, v6
	v_lshlrev_b32_e32 v6, 16, v7
	v_and_b32_e32 v7, 0xffff0000, v7
	v_lshlrev_b32_e32 v10, 16, v8
	v_and_b32_e32 v11, 0xffff0000, v8
	v_lshlrev_b32_e32 v8, 16, v9
	v_and_b32_e32 v9, 0xffff0000, v9
	v_pk_mul_f32 v[6:7], v[6:7], s[36:37] op_sel_hi:[1,0]
	v_pk_mul_f32 v[8:9], v[8:9], s[36:37] op_sel_hi:[1,0]
	v_cvt_pk_bf16_f32 v103, v6, v7
	v_cvt_pk_bf16_f32 v105, v8, v9
	global_load_dwordx4 v[6:9], v[4:5], off offset:64
	v_pk_mul_f32 v[2:3], v[2:3], s[36:37] op_sel_hi:[1,0]
	v_pk_mul_f32 v[10:11], v[10:11], s[36:37] op_sel_hi:[1,0]
	v_cvt_pk_bf16_f32 v102, v2, v3
	v_cvt_pk_bf16_f32 v104, v10, v11
	s_waitcnt vmcnt(0)
	v_lshlrev_b32_e32 v2, 16, v6
	v_and_b32_e32 v3, 0xffff0000, v6
	v_lshlrev_b32_e32 v6, 16, v7
	v_and_b32_e32 v7, 0xffff0000, v7
	v_lshlrev_b32_e32 v10, 16, v8
	v_and_b32_e32 v11, 0xffff0000, v8
	v_lshlrev_b32_e32 v8, 16, v9
	v_and_b32_e32 v9, 0xffff0000, v9
	v_pk_mul_f32 v[6:7], v[6:7], s[36:37] op_sel_hi:[1,0]
	v_pk_mul_f32 v[8:9], v[8:9], s[36:37] op_sel_hi:[1,0]
	v_cvt_pk_bf16_f32 v107, v6, v7
	v_cvt_pk_bf16_f32 v109, v8, v9
	global_load_dwordx4 v[6:9], v[4:5], off offset:96
	v_pk_mul_f32 v[2:3], v[2:3], s[36:37] op_sel_hi:[1,0]
	v_pk_mul_f32 v[10:11], v[10:11], s[36:37] op_sel_hi:[1,0]
	v_cvt_pk_bf16_f32 v106, v2, v3
	v_cvt_pk_bf16_f32 v108, v10, v11
	s_waitcnt vmcnt(0)
	v_lshlrev_b32_e32 v2, 16, v6
	v_and_b32_e32 v3, 0xffff0000, v6
	v_lshlrev_b32_e32 v6, 16, v7
	v_and_b32_e32 v7, 0xffff0000, v7
	v_lshlrev_b32_e32 v10, 16, v8
	v_and_b32_e32 v11, 0xffff0000, v8
	v_lshlrev_b32_e32 v8, 16, v9
	v_and_b32_e32 v9, 0xffff0000, v9
	v_pk_mul_f32 v[6:7], v[6:7], s[36:37] op_sel_hi:[1,0]
	v_pk_mul_f32 v[8:9], v[8:9], s[36:37] op_sel_hi:[1,0]
	v_cvt_pk_bf16_f32 v111, v6, v7
	v_cvt_pk_bf16_f32 v113, v8, v9
	global_load_dwordx4 v[6:9], v[4:5], off offset:128
	v_pk_mul_f32 v[2:3], v[2:3], s[36:37] op_sel_hi:[1,0]
	v_pk_mul_f32 v[10:11], v[10:11], s[36:37] op_sel_hi:[1,0]
	v_cvt_pk_bf16_f32 v110, v2, v3
	v_cvt_pk_bf16_f32 v112, v10, v11
	s_waitcnt vmcnt(0)
	v_lshlrev_b32_e32 v2, 16, v6
	v_and_b32_e32 v3, 0xffff0000, v6
	v_lshlrev_b32_e32 v6, 16, v7
	v_and_b32_e32 v7, 0xffff0000, v7
	v_lshlrev_b32_e32 v10, 16, v8
	v_and_b32_e32 v11, 0xffff0000, v8
	v_lshlrev_b32_e32 v8, 16, v9
	v_and_b32_e32 v9, 0xffff0000, v9
	v_pk_mul_f32 v[6:7], v[6:7], s[36:37] op_sel_hi:[1,0]
	v_pk_mul_f32 v[8:9], v[8:9], s[36:37] op_sel_hi:[1,0]
	v_cvt_pk_bf16_f32 v115, v6, v7
	v_cvt_pk_bf16_f32 v117, v8, v9
	global_load_dwordx4 v[6:9], v[4:5], off offset:160
	v_pk_mul_f32 v[2:3], v[2:3], s[36:37] op_sel_hi:[1,0]
	v_pk_mul_f32 v[10:11], v[10:11], s[36:37] op_sel_hi:[1,0]
	v_cvt_pk_bf16_f32 v114, v2, v3
	v_cvt_pk_bf16_f32 v116, v10, v11
	s_waitcnt vmcnt(0)
	v_lshlrev_b32_e32 v2, 16, v6
	v_and_b32_e32 v3, 0xffff0000, v6
	v_lshlrev_b32_e32 v6, 16, v7
	v_and_b32_e32 v7, 0xffff0000, v7
	v_lshlrev_b32_e32 v10, 16, v8
	v_and_b32_e32 v11, 0xffff0000, v8
	v_lshlrev_b32_e32 v8, 16, v9
	v_and_b32_e32 v9, 0xffff0000, v9
	v_pk_mul_f32 v[6:7], v[6:7], s[36:37] op_sel_hi:[1,0]
	v_pk_mul_f32 v[8:9], v[8:9], s[36:37] op_sel_hi:[1,0]
	v_cvt_pk_bf16_f32 v119, v6, v7
	v_cvt_pk_bf16_f32 v121, v8, v9
	global_load_dwordx4 v[6:9], v[4:5], off offset:192
	v_pk_mul_f32 v[2:3], v[2:3], s[36:37] op_sel_hi:[1,0]
	v_pk_mul_f32 v[10:11], v[10:11], s[36:37] op_sel_hi:[1,0]
	v_cvt_pk_bf16_f32 v118, v2, v3
	v_cvt_pk_bf16_f32 v120, v10, v11
	s_waitcnt vmcnt(0)
	v_lshlrev_b32_e32 v2, 16, v6
	v_and_b32_e32 v3, 0xffff0000, v6
	v_lshlrev_b32_e32 v6, 16, v7
	v_and_b32_e32 v7, 0xffff0000, v7
	v_lshlrev_b32_e32 v10, 16, v8
	v_and_b32_e32 v11, 0xffff0000, v8
	v_lshlrev_b32_e32 v8, 16, v9
	v_and_b32_e32 v9, 0xffff0000, v9
	v_pk_mul_f32 v[6:7], v[6:7], s[36:37] op_sel_hi:[1,0]
	v_pk_mul_f32 v[8:9], v[8:9], s[36:37] op_sel_hi:[1,0]
	v_cvt_pk_bf16_f32 v123, v6, v7
	v_cvt_pk_bf16_f32 v125, v8, v9
	global_load_dwordx4 v[6:9], v[4:5], off offset:224
	v_pk_mul_f32 v[2:3], v[2:3], s[36:37] op_sel_hi:[1,0]
	v_pk_mul_f32 v[10:11], v[10:11], s[36:37] op_sel_hi:[1,0]
	v_cvt_pk_bf16_f32 v122, v2, v3
	v_cvt_pk_bf16_f32 v124, v10, v11
	s_waitcnt vmcnt(0)
	v_lshlrev_b32_e32 v2, 16, v6
	v_and_b32_e32 v3, 0xffff0000, v6
	v_lshlrev_b32_e32 v6, 16, v7
	v_and_b32_e32 v7, 0xffff0000, v7
	v_lshlrev_b32_e32 v10, 16, v8
	v_and_b32_e32 v11, 0xffff0000, v8
	v_lshlrev_b32_e32 v8, 16, v9
	v_and_b32_e32 v9, 0xffff0000, v9
	v_pk_mul_f32 v[6:7], v[6:7], s[36:37] op_sel_hi:[1,0]
	v_pk_mul_f32 v[8:9], v[8:9], s[36:37] op_sel_hi:[1,0]
	v_cvt_pk_bf16_f32 v127, v6, v7
	v_cvt_pk_bf16_f32 v129, v8, v9
	v_lshl_add_u64 v[6:7], s[44:45], 0, v[0:1]
	v_lshlrev_b32_e32 v8, 6, v76
	v_mov_b32_e32 v9, v81
	v_pk_mul_f32 v[2:3], v[2:3], s[36:37] op_sel_hi:[1,0]
	v_pk_mul_f32 v[10:11], v[10:11], s[36:37] op_sel_hi:[1,0]
	v_lshl_add_u64 v[6:7], v[6:7], 0, v[8:9]
	v_cvt_pk_bf16_f32 v126, v2, v3
	v_cvt_pk_bf16_f32 v128, v10, v11
	global_load_dwordx4 v[0:3], v[4:5], off offset:256
	global_load_dwordx4 v[10:13], v[4:5], off offset:320
	v_add_co_u32_e32 v8, vcc, s1, v6
	v_lshl_add_u64 v[26:27], v[6:7], 0, s[6:7]
	s_nop 0
	v_addc_co_u32_e32 v9, vcc, 0, v7, vcc
	global_load_dwordx4 v[14:17], v[8:9], off
	global_load_dwordx4 v[18:21], v[26:27], off offset:48
	global_load_dwordx4 v[22:25], v[26:27], off offset:32
	s_nop 0
	global_load_dwordx4 v[26:29], v[26:27], off offset:16
	s_mov_b64 s[6:7], 0x200080
	s_waitcnt vmcnt(5)
	v_lshlrev_b32_e32 v30, 16, v0
	s_waitcnt vmcnt(4)
	v_lshlrev_b32_e32 v32, 16, v10
	v_and_b32_e32 v33, 0xffff0000, v10
	v_and_b32_e32 v31, 0xffff0000, v0
	s_waitcnt vmcnt(3)
; DI void unpack8(const u32x4 w, float (&f)[8]) { f[0] = bflo(w.x); f[1] = bfhi(w.x); f[2] = bflo(w.y); f[3] = bfhi(w.y); f[4] = bflo(w.z); f[5] = bfhi(w.z); f[6] = bflo(w.w); f[7] = bfhi(w.w); }
; DI u32x4 pack8f(const float (&f)[8]) { u32x4 w; w.x = pk2(f[0], f[1]); w.y = pk2(f[2], f[3]); w.z = pk2(f[4], f[5]); w.w = pk2(f[6], f[7]); return w; }
; DI void attn_item(CArgs& a, LAS unsigned char* lds, int l, int b, int h, int qb, int tid_, int wave, int lane_) {
;     ...
;       for (int ks = 8; ks < 10; ++ks) { float x1[8], x2[8], o1[8], o2[8]; unpack8(*(const u32x4*)(qp + 16 * ks + 8 * hh), x1); unpack8(*(const u32x4*)(qp + 16 * (ks + 2) + 8 * hh), x2);
;           const f32x2* cs = (const f32x2*)(a.ws + WS_ROPE) + tq * 32 + 16 * (ks - 8) + 8 * hh;
; #pragma unroll
;           for (int e = 0; e < 8; ++e) { const f32x2 t = cs[e]; o1[e] = (x1[e] * t.x - x2[e] * t.y) * sc; o2[e] = (x1[e] * t.y + x2[e] * t.x) * sc; }
;           qf[ks] = __builtin_bit_cast(bf16x8, pack8f(o1)); qf[ks + 2] = __builtin_bit_cast(bf16x8, pack8f(o2)); } }
	v_mov_b32_e32 v34, v15
	v_mov_b32_e32 v35, v17
	v_mov_b32_e32 v15, v16
	v_pk_mul_f32 v[16:17], v[14:15], v[32:33]
	v_pk_mul_f32 v[32:33], v[34:35], v[32:33]
	v_pk_fma_f32 v[16:17], v[34:35], v[30:31], v[16:17]
	v_pk_fma_f32 v[14:15], v[14:15], v[30:31], v[32:33] neg_lo:[0,0,1] neg_hi:[0,0,1]
	v_lshlrev_b32_e32 v10, 16, v11
	v_and_b32_e32 v11, 0xffff0000, v11
	s_waitcnt vmcnt(0)
	v_mov_b32_e32 v30, v27
	v_mov_b32_e32 v31, v29
	v_mov_b32_e32 v27, v28
	v_lshlrev_b32_e32 v0, 16, v1
	v_and_b32_e32 v1, 0xffff0000, v1
	v_pk_mul_f32 v[28:29], v[26:27], v[10:11]
	v_pk_mul_f32 v[10:11], v[30:31], v[10:11]
	v_pk_fma_f32 v[28:29], v[30:31], v[0:1], v[28:29]
	v_pk_fma_f32 v[0:1], v[26:27], v[0:1], v[10:11] neg_lo:[0,0,1] neg_hi:[0,0,1]
	v_lshlrev_b32_e32 v26, 16, v12
	v_and_b32_e32 v27, 0xffff0000, v12
	v_mov_b32_e32 v30, v23
	v_mov_b32_e32 v31, v25
	v_mov_b32_e32 v23, v24
	v_lshlrev_b32_e32 v10, 16, v2
	v_and_b32_e32 v11, 0xffff0000, v2
	v_pk_mul_f32 v[24:25], v[22:23], v[26:27]
	v_pk_mul_f32 v[26:27], v[30:31], v[26:27]
	v_pk_fma_f32 v[24:25], v[30:31], v[10:11], v[24:25]
	v_pk_fma_f32 v[10:11], v[22:23], v[10:11], v[26:27] neg_lo:[0,0,1] neg_hi:[0,0,1]
	v_lshlrev_b32_e32 v12, 16, v13
	v_and_b32_e32 v13, 0xffff0000, v13
	v_mov_b32_e32 v22, v19
	v_mov_b32_e32 v23, v21
	v_mov_b32_e32 v19, v20
	v_lshlrev_b32_e32 v2, 16, v3
	v_and_b32_e32 v3, 0xffff0000, v3
	v_pk_mul_f32 v[20:21], v[18:19], v[12:13]
	v_pk_mul_f32 v[12:13], v[22:23], v[12:13]
	v_pk_fma_f32 v[20:21], v[22:23], v[2:3], v[20:21]
	v_pk_fma_f32 v[2:3], v[18:19], v[2:3], v[12:13] neg_lo:[0,0,1] neg_hi:[0,0,1]
	v_pk_mul_f32 v[0:1], v[0:1], s[36:37] op_sel_hi:[1,0]
	v_pk_mul_f32 v[10:11], v[10:11], s[36:37] op_sel_hi:[1,0]
	v_pk_mul_f32 v[2:3], v[2:3], s[36:37] op_sel_hi:[1,0]
	v_cvt_pk_bf16_f32 v131, v0, v1
	v_cvt_pk_bf16_f32 v132, v10, v11
	v_cvt_pk_bf16_f32 v133, v2, v3
	global_load_dwordx4 v[0:3], v[4:5], off offset:288
	global_load_dwordx4 v[10:13], v[4:5], off offset:352
	v_pk_mul_f32 v[16:17], v[16:17], s[36:37] op_sel_hi:[1,0]
	v_pk_mul_f32 v[14:15], v[14:15], s[36:37] op_sel_hi:[1,0]
	v_pk_mul_f32 v[24:25], v[24:25], s[36:37] op_sel_hi:[1,0]
	v_pk_mul_f32 v[20:21], v[20:21], s[36:37] op_sel_hi:[1,0]
	v_lshl_add_u64 v[22:23], v[6:7], 0, s[6:7]
	v_cvt_pk_bf16_f32 v130, v14, v15
	v_cvt_pk_bf16_f32 v134, v16, v17
	v_cvt_pk_bf16_f32 v136, v24, v25
	v_cvt_pk_bf16_f32 v137, v20, v21
	global_load_dwordx4 v[4:7], v[8:9], off offset:128
	global_load_dwordx4 v[14:17], v[22:23], off offset:48
	global_load_dwordx4 v[18:21], v[22:23], off offset:32
	s_nop 0
	global_load_dwordx4 v[22:25], v[22:23], off offset:16
	v_pk_mul_f32 v[28:29], v[28:29], s[36:37] op_sel_hi:[1,0]
	v_mov_b32_e32 v30, v81
	v_cvt_pk_bf16_f32 v135, v28, v29
	v_mov_b32_e32 v31, v81
	v_mov_b32_e32 v32, v81
	v_mov_b32_e32 v33, v81
	v_mov_b32_e32 v34, v81
	v_mov_b32_e32 v35, v81
	v_cmp_gt_u32_e64 s[6:7], 32, v74
	s_waitcnt vmcnt(5)
	v_lshlrev_b32_e32 v8, 16, v0
	s_waitcnt vmcnt(4)
	v_lshlrev_b32_e32 v26, 16, v10
	v_and_b32_e32 v27, 0xffff0000, v10
	v_and_b32_e32 v9, 0xffff0000, v0
	v_lshlrev_b32_e32 v0, 16, v1
	v_and_b32_e32 v1, 0xffff0000, v1
	s_waitcnt vmcnt(3)
	v_mov_b32_e32 v28, v5
	v_mov_b32_e32 v29, v7
	v_mov_b32_e32 v5, v6
	v_pk_mul_f32 v[6:7], v[4:5], v[26:27]
	v_pk_mul_f32 v[26:27], v[28:29], v[26:27]
	v_pk_fma_f32 v[6:7], v[28:29], v[8:9], v[6:7]
	v_pk_fma_f32 v[4:5], v[4:5], v[8:9], v[26:27] neg_lo:[0,0,1] neg_hi:[0,0,1]
	v_lshlrev_b32_e32 v8, 16, v11
	v_and_b32_e32 v9, 0xffff0000, v11
	s_waitcnt vmcnt(0)
; #define LAS __attribute__((address_space(3)))
; DI void attn_store(LAS unsigned char* lds, int tid, const u32x4 (&kr)[3], const u32x4 (&vr)[2]) {
;     LAS bf16_t* Ks = (LAS bf16_t*)(lds + AT_KS); LAS bf16_t* Rs = (LAS bf16_t*)(lds + AT_RS); LAS bf16_t* Vs = (LAS bf16_t*)(lds + AT_VS);
; #pragma unroll
;     for (int i = 0; i < 2; ++i) { const int ck = tid + 512 * i, row = ck >> 4, cc = ck & 15; *(LAS u32x4*)(Ks + row * 136 + 8 * cc) = kr[i]; }
;     { const int row = tid >> 3, cc = tid & 7; *(LAS u32x4*)(Rs + row * 72 + 8 * cc) = kr[2]; }
; #pragma unroll
;     for (int i = 0; i < 2; ++i) { const int cv = tid + 512 * i, v = cv >> 3, cc = cv & 7;
;         LAS bf16_t* d = Vs + v * 72 + 16 * (cc >> 1) + 4 * (cc & 1);
;         *(LAS u32x2*)d = (u32x2){vr[i].x, vr[i].y}; *(LAS u32x2*)(d + 8) = (u32x2){vr[i].z, vr[i].w}; }
; }
; DI void attn_item(CArgs& a, LAS unsigned char* lds, int l, int b, int h, int qb, int tid_, int wave, int lane_) {
;     ...
;     const int NT = 4 * qb + 4;
;     float m_run = -INFINITY, l_run = 0.f; f32x16 o[4]; o[0] = zero16(); o[1] = zero16(); o[2] = zero16(); o[3] = zero16();
;     u32x4 kr[3], vr[2];
;     attn_load(a, b, h, 0, F, kr, vr);
;     attn_store(lds, tid, kr, vr);
;     attn_load(a, b, h, 1, F, kr, vr);
;     __syncthreads();
	v_mov_b32_e32 v10, v23
	v_mov_b32_e32 v11, v25
	v_mov_b32_e32 v23, v24
	v_pk_mul_f32 v[24:25], v[22:23], v[8:9]
	v_pk_mul_f32 v[8:9], v[10:11], v[8:9]
	v_pk_fma_f32 v[24:25], v[10:11], v[0:1], v[24:25]
	v_pk_fma_f32 v[0:1], v[22:23], v[0:1], v[8:9] neg_lo:[0,0,1] neg_hi:[0,0,1]
	v_lshlrev_b32_e32 v10, 16, v12
	v_and_b32_e32 v11, 0xffff0000, v12
	v_mov_b32_e32 v22, v19
	v_mov_b32_e32 v23, v21
	v_mov_b32_e32 v19, v20
	v_lshlrev_b32_e32 v8, 16, v2
	v_and_b32_e32 v9, 0xffff0000, v2
	v_pk_mul_f32 v[20:21], v[18:19], v[10:11]
	v_pk_mul_f32 v[10:11], v[22:23], v[10:11]
	v_pk_fma_f32 v[20:21], v[22:23], v[8:9], v[20:21]
	v_pk_fma_f32 v[8:9], v[18:19], v[8:9], v[10:11] neg_lo:[0,0,1] neg_hi:[0,0,1]
	v_lshlrev_b32_e32 v10, 16, v13
	v_and_b32_e32 v11, 0xffff0000, v13
	v_mov_b32_e32 v12, v15
	v_mov_b32_e32 v13, v17
	v_mov_b32_e32 v15, v16
	v_lshlrev_b32_e32 v2, 16, v3
	v_and_b32_e32 v3, 0xffff0000, v3
	v_pk_mul_f32 v[16:17], v[14:15], v[10:11]
	v_pk_mul_f32 v[10:11], v[12:13], v[10:11]
	v_pk_fma_f32 v[16:17], v[12:13], v[2:3], v[16:17]
	v_pk_fma_f32 v[2:3], v[14:15], v[2:3], v[10:11] neg_lo:[0,0,1] neg_hi:[0,0,1]
	v_pk_mul_f32 v[6:7], v[6:7], s[36:37] op_sel_hi:[1,0]
	v_pk_mul_f32 v[4:5], v[4:5], s[36:37] op_sel_hi:[1,0]
	v_pk_mul_f32 v[24:25], v[24:25], s[36:37] op_sel_hi:[1,0]
	v_pk_mul_f32 v[0:1], v[0:1], s[36:37] op_sel_hi:[1,0]
	v_pk_mul_f32 v[20:21], v[20:21], s[36:37] op_sel_hi:[1,0]
	v_pk_mul_f32 v[8:9], v[8:9], s[36:37] op_sel_hi:[1,0]
	v_pk_mul_f32 v[16:17], v[16:17], s[36:37] op_sel_hi:[1,0]
	v_pk_mul_f32 v[2:3], v[2:3], s[36:37] op_sel_hi:[1,0]
	v_cvt_pk_bf16_f32 v138, v4, v5
	v_cvt_pk_bf16_f32 v139, v0, v1
	v_cvt_pk_bf16_f32 v140, v8, v9
	v_cvt_pk_bf16_f32 v141, v2, v3
	v_cvt_pk_bf16_f32 v142, v6, v7
	v_cvt_pk_bf16_f32 v143, v24, v25
	v_cvt_pk_bf16_f32 v144, v20, v21
	v_cvt_pk_bf16_f32 v145, v16, v17
	v_mov_b32_e32 v0, v81
	v_mov_b32_e32 v1, v81
	v_mov_b32_e32 v2, v81
	v_mov_b32_e32 v3, v81
	v_mov_b32_e32 v4, v81
	v_mov_b32_e32 v5, v81
	v_mov_b32_e32 v6, v81
	v_mov_b32_e32 v7, v81
	v_mov_b32_e32 v8, v81
	v_mov_b32_e32 v9, v81
	v_mov_b32_e32 v10, v81
	v_mov_b32_e32 v11, v81
	v_mov_b32_e32 v12, v81
	v_mov_b32_e32 v13, v81
	v_mov_b32_e32 v14, v81
	v_mov_b32_e32 v15, v81
	v_mov_b32_e32 v16, v81
	v_mov_b32_e32 v17, v81
	v_mov_b32_e32 v18, v81
	v_mov_b32_e32 v19, v81
	v_mov_b32_e32 v20, v81
	v_mov_b32_e32 v21, v81
	v_mov_b32_e32 v22, v81
	v_mov_b32_e32 v23, v81
	v_mov_b32_e32 v24, v81
	v_mov_b32_e32 v25, v81
	v_mov_b32_e32 v26, v81
	v_mov_b32_e32 v27, v81
	v_mov_b32_e32 v28, v81
	v_mov_b32_e32 v29, v81
	global_load_dwordx4 v[146:149], v64, s[18:19]
	global_load_dwordx4 v[150:153], v66, s[18:19]
	global_load_dwordx4 v[154:157], v68, s[16:17]
	global_load_dwordx4 v[158:161], v70, s[2:3]
	global_load_dwordx4 v[162:165], v72, s[2:3]
	s_lshl_b32 s36, s0, 2
	s_movk_i32 s0, 0x110
	v_mul_lo_u32 v175, v175, s0
	v_add_u32_e32 v177, v176, v175
	s_add_i32 s47, s36, 4
	s_add_i32 s16, s5, 0x100
	s_mov_b32 s2, 0
	s_waitcnt vmcnt(4)
	ds_write_b128 v177, v[146:149]
	v_add_u32_e32 v146, 0x200, v77
	v_lshrrev_b32_e32 v147, 4, v146
	v_mul_lo_u32 v189, v147, s0
	v_add_u32_e32 v147, v176, v189
	s_waitcnt vmcnt(3)
	ds_write_b128 v147, v[150:153]
	v_lshrrev_b32_e32 v147, 3, v77
	v_lshlrev_b32_e32 v77, 2, v77
	v_and_b32_e32 v77, 4, v77
	s_movk_i32 s0, 0x90
	v_lshlrev_b32_e32 v193, 1, v77
	v_mul_lo_u32 v190, v147, s0
	v_add3_u32 v77, 0, v192, v193
	v_add_u32_e32 v78, v77, v190
	v_add_u32_e32 v78, 0x6800, v78
	s_waitcnt vmcnt(1)
	ds_write2_b64 v78, v[158:159], v[160:161] offset1:2
	v_lshrrev_b32_e32 v78, 3, v146
	v_mul_lo_u32 v194, v78, s0
	v_add_u32_e32 v77, v77, v194
	v_add3_u32 v79, 0, v190, v191
	v_add_u32_e32 v77, 0x6800, v77
	ds_write_b128 v79, v[154:157] offset:17408
	s_waitcnt vmcnt(0)
	ds_write2_b64 v77, v[162:163], v[164:165] offset1:2
	global_load_dwordx4 v[146:149], v64, s[52:53]
	global_load_dwordx4 v[150:153], v66, s[52:53]
	global_load_dwordx4 v[154:157], v68, s[60:61]
	global_load_dwordx4 v[158:161], v70, s[62:63]
	global_load_dwordx4 v[162:165], v72, s[62:63]
	v_mad_u32_u24 v201, v169, s0, v222
	v_lshl_add_u64 v[176:177], s[20:21], 0, v[70:71]
	s_waitcnt lgkmcnt(0)
	s_barrier
